# S5 pass 1: item loads issued right after the item barrier with the rstd block's loads behind them (one round trip instead of two); rstd block registers renamed
# baseline (speedup 1.0000x reference)
.LBB0_172:
	s_and_b32 s0, s17, 56
	s_ashr_i32 s11, s10, 31
	s_add_i32 s0, s0, s16
	s_lshl_b64 s[12:13], s[10:11], 12
	v_lshl_or_b32 v2, s18, 7, v111
	v_or_b32_e32 v2, s12, v2
	s_lshl_b32 s12, s0, 4
	v_mov_b32_e32 v3, s13
	s_ashr_i32 s13, s12, 31
	s_add_i32 s1, s0, s15
	v_lshl_add_u64 v[6:7], s[12:13], 1, v[114:115]
	s_waitcnt vmcnt(3)
	v_or_b32_e32 v10, s12, v129
	s_lshl_b32 s12, s1, 1
	v_or_b32_e32 v2, v2, v110
	s_or_b32 s20, s12, 1
	v_lshlrev_b64 v[8:9], 11, v[2:3]
	v_ashrrev_i32_e32 v11, 31, v10
	s_ashr_i32 s21, s20, 31
	v_lshl_add_u64 v[2:3], v[6:7], 0, v[8:9]
	v_lshl_add_u64 v[10:11], v[10:11], 2, s[6:7]
	s_lshl_b64 s[20:21], s[20:21], 11
	global_load_dwordx4 v[2:5], v[2:3], off
	s_nop 0
	global_load_dwordx4 v[78:81], v[10:11], off
	global_load_dwordx4 v[66:69], v[10:11], off offset:16
	v_lshl_add_u64 v[10:11], v[116:117], 0, s[20:21]
	s_ashr_i32 s13, s12, 31
	v_lshl_add_u64 v[12:13], v[10:11], 0, v[154:155]
	s_lshl_b64 s[12:13], s[12:13], 11
	global_load_dwordx4 v[74:77], v[12:13], off
	v_lshl_add_u64 v[12:13], v[116:117], 0, s[12:13]
	s_waitcnt vmcnt(6)
	v_lshl_add_u64 v[14:15], v[12:13], 0, v[154:155]
	global_load_dwordx4 v[70:73], v[14:15], off
	v_lshl_or_b32 v14, s1, 7, v130
	v_ashrrev_i32_e32 v15, 31, v14
	v_lshl_add_u64 v[14:15], v[14:15], 2, s[8:9]
	global_load_dwordx2 v[124:125], v[14:15], off
	v_or_b32_e32 v16, 0x8000, v8
	v_mov_b32_e32 v17, v9
	s_waitcnt vmcnt(7)
	v_or_b32_e32 v18, 0x10000, v8
	v_mov_b32_e32 v19, v9
	v_or_b32_e32 v20, 0x18000, v8
	v_mov_b32_e32 v21, v9
	s_waitcnt vmcnt(6)
	v_or_b32_e32 v22, 0x20000, v8
	v_mov_b32_e32 v23, v9
	v_or_b32_e32 v24, 0x28000, v8
	v_mov_b32_e32 v25, v9
	v_or_b32_e32 v26, 0x30000, v8
	v_mov_b32_e32 v27, v9
	v_or_b32_e32 v8, 0x38000, v8
	v_lshl_add_u64 v[16:17], v[6:7], 0, v[16:17]
	v_lshl_add_u64 v[18:19], v[6:7], 0, v[18:19]
	v_lshl_add_u64 v[20:21], v[6:7], 0, v[20:21]
	v_lshl_add_u64 v[22:23], v[6:7], 0, v[22:23]
	v_lshl_add_u64 v[24:25], v[6:7], 0, v[24:25]
	v_lshl_add_u64 v[26:27], v[6:7], 0, v[26:27]
	v_lshl_add_u64 v[6:7], v[6:7], 0, v[8:9]
	global_load_dwordx2 v[122:123], v[14:15], off offset:256
	global_load_dwordx4 v[106:109], v[16:17], off
	global_load_dwordx4 v[102:105], v[18:19], off
	global_load_dwordx4 v[98:101], v[20:21], off
	global_load_dwordx4 v[94:97], v[22:23], off
	global_load_dwordx4 v[90:93], v[24:25], off
	global_load_dwordx4 v[86:89], v[26:27], off
	global_load_dwordx4 v[82:85], v[6:7], off
	v_lshl_add_u64 v[6:7], v[12:13], 0, v[118:119]
	v_lshl_add_u64 v[8:9], v[10:11], 0, v[118:119]
	global_load_dwordx4 v[62:65], v[6:7], off
	global_load_dwordx4 v[58:61], v[8:9], off
	s_and_saveexec_b64 s[12:13], vcc
	s_cbranch_execz .Lrsb1_skip
	s_lshl_b32 s11, s10, 12
	v_or_b32_e32 v28, s18, v126
	v_lshl_add_u32 v28, v28, 7, s11
	v_or_b32_e32 v28, v28, v127
	v_ashrrev_i32_e32 v29, 31, v28
	v_lshlrev_b64 v[28:29], 7, v[28:29]
	v_lshl_add_u64 v[40:41], s[4:5], 0, v[28:29]
	global_load_dwordx4 v[28:31], v[40:41], off
	global_load_dwordx4 v[32:35], v[40:41], off offset:16
	global_load_dwordx4 v[36:39], v[40:41], off offset:32
	s_nop 0
	global_load_dwordx4 v[40:43], v[40:41], off offset:48
	s_waitcnt vmcnt(3)
	v_mov_b32_e32 v44, v29
	v_mov_b32_e32 v45, v30
	v_mov_b32_e32 v29, v31
	s_waitcnt vmcnt(2)
	v_mov_b32_e32 v30, v33
	v_mov_b32_e32 v31, v34
	v_mov_b32_e32 v33, v35
	s_waitcnt vmcnt(1)
	v_add_f32_e32 v34, v36, v37
	v_add_f32_e32 v36, v38, v39
	s_waitcnt vmcnt(0)
	v_mov_b32_e32 v35, v42
	v_mov_b32_e32 v37, v43
	v_pk_add_f32 v[28:29], v[44:45], v[28:29]
	v_pk_add_f32 v[30:31], v[30:31], v[32:33]
	v_pk_add_f32 v[32:33], v[34:35], v[36:37]
	v_add_f32_e32 v34, v28, v29
	v_pk_add_f32 v[28:29], v[30:31], v[30:31] op_sel:[0,1] op_sel_hi:[1,0]
	v_mov_b32_e32 v39, v40
	v_add_f32_e32 v38, 0, v34
	v_mov_b32_e32 v29, v41
	v_pk_add_f32 v[28:29], v[38:39], v[28:29]
	s_nop 0
	v_pk_add_f32 v[28:29], v[28:29], v[32:33]
	s_nop 0
	v_add_f32_e32 v28, v28, v29
	v_fmamk_f32 v28, v28, 0x3a800000, v225
	v_mul_f32_e32 v29, 0x4b800000, v28
	v_cmp_gt_f32_e64 s[20:21], s90, v28
	s_nop 1
	v_cndmask_b32_e64 v28, v28, v29, s[20:21]
	v_rsq_f32_e32 v28, v28
	s_nop 0
	v_mul_f32_e32 v29, 0x45800000, v28
	v_cndmask_b32_e64 v28, v28, v29, s[20:21]
	ds_write_b32 v128, v28
.Lrsb1_skip:
	s_or_b64 exec, exec, s[12:13]
	s_waitcnt lgkmcnt(0)
	s_barrier
	ds_read_b32 v6, v113
	s_add_i32 s14, s14, s86
	s_add_i32 s17, s17, s52
	s_cmpk_lt_i32 s14, 0x200
	s_waitcnt vmcnt(15)
	v_lshlrev_b32_e32 v7, 16, v2
	v_and_b32_e32 v2, 0xffff0000, v2
	v_lshlrev_b32_e32 v8, 16, v3
	v_and_b32_e32 v3, 0xffff0000, v3
	v_lshlrev_b32_e32 v9, 16, v4
	v_and_b32_e32 v4, 0xffff0000, v4
	v_lshlrev_b32_e32 v10, 16, v5
	v_and_b32_e32 v5, 0xffff0000, v5
	s_waitcnt lgkmcnt(0)
	v_mul_f32_e32 v2, v6, v2
	v_mul_f32_e32 v4, v6, v4
	v_mul_f32_e32 v10, v6, v10
	v_mul_f32_e32 v3, v6, v3
	v_mul_f32_e32 v5, v6, v5
	v_mul_f32_e32 v7, v6, v7
	v_mul_f32_e32 v9, v6, v9
	v_mul_f32_e32 v8, v6, v8
	s_waitcnt vmcnt(14)
	v_mul_f32_e32 v2, v79, v2
	s_waitcnt vmcnt(13)
	v_mul_f32_e32 v4, v67, v4
	v_mul_f32_e32 v10, v68, v10
	v_mul_f32_e32 v3, v81, v3
	v_mul_f32_e32 v5, v69, v5
	v_mul_f32_e32 v7, v78, v7
	v_mul_f32_e32 v9, v66, v9
	v_mul_f32_e32 v8, v80, v8
	v_cvt_pk_bf16_f32 v2, v7, v2
	v_cvt_pk_bf16_f32 v3, v8, v3
	v_cvt_pk_bf16_f32 v4, v9, v4
	v_cvt_pk_bf16_f32 v5, v10, v5
	s_waitcnt vmcnt(12)
	v_mfma_f32_32x32x16_bf16 v[26:41], v[2:5], v[74:77], 0
	s_waitcnt vmcnt(11)
	v_mfma_f32_32x32x16_bf16 v[10:25], v[2:5], v[70:73], 0
	s_nop 9
	v_mov_b32_e32 v6, v26
	s_waitcnt vmcnt(10)
	v_mov_b32_e32 v26, v125
	v_mov_b32_e32 v132, v40
	s_waitcnt vmcnt(8)
	v_and_b32_e32 v40, 0xffff0000, v109
	s_waitcnt vmcnt(0)
	v_mfma_f32_32x32x16_bf16 v[42:57], v[2:5], v[58:61], 0
	v_mov_b32_e32 v7, v10
	v_fma_f32 v6, v125, 0, v6
	v_fma_f32 v7, -v125, 0, v7
	v_mov_b32_e32 v10, v27
	v_fma_f32 v6, v124, 0, v6
	v_fma_f32 v7, v124, 0, v7
	v_pk_fma_f32 v[8:9], v[124:125], v[6:7], v[10:11] op_sel:[1,1,0] op_sel_hi:[1,0,1] neg_hi:[1,0,0]
	v_xor_b32_e32 v27, 0x80000000, v125
	v_pk_fma_f32 v[6:7], v[124:125], v[6:7], v[8:9] op_sel_hi:[0,1,1]
	v_mov_b32_e32 v8, v28
	v_mov_b32_e32 v9, v12
	v_pk_fma_f32 v[8:9], v[124:125], v[6:7], v[8:9] op_sel:[1,1,0] op_sel_hi:[1,0,1] neg_hi:[1,0,0]
	v_mov_b32_e32 v12, v29
	v_pk_fma_f32 v[6:7], v[124:125], v[6:7], v[8:9] op_sel_hi:[0,1,1]
	v_pk_fma_f32 v[8:9], v[124:125], v[6:7], v[12:13] op_sel:[1,1,0] op_sel_hi:[1,0,1] neg_hi:[1,0,0]
	v_mov_b32_e32 v135, v50
	v_pk_fma_f32 v[6:7], v[124:125], v[6:7], v[8:9] op_sel_hi:[0,1,1]
	v_mov_b32_e32 v8, v30
	v_mov_b32_e32 v9, v14
	v_pk_fma_f32 v[8:9], v[124:125], v[6:7], v[8:9] op_sel:[1,1,0] op_sel_hi:[1,0,1] neg_hi:[1,0,0]
	v_mov_b32_e32 v14, v31
	v_pk_fma_f32 v[6:7], v[124:125], v[6:7], v[8:9] op_sel_hi:[0,1,1]
	v_pk_fma_f32 v[8:9], v[124:125], v[6:7], v[14:15] op_sel:[1,1,0] op_sel_hi:[1,0,1] neg_hi:[1,0,0]
	v_mov_b32_e32 v30, v18
	v_pk_fma_f32 v[6:7], v[124:125], v[6:7], v[8:9] op_sel_hi:[0,1,1]
	v_mov_b32_e32 v8, v32
	v_mov_b32_e32 v9, v16
	v_pk_fma_f32 v[8:9], v[124:125], v[6:7], v[8:9] op_sel:[1,1,0] op_sel_hi:[1,0,1] neg_hi:[1,0,0]
	v_mov_b32_e32 v32, v17
	v_pk_fma_f32 v[28:29], v[124:125], v[6:7], v[8:9] op_sel_hi:[0,1,1]
	v_mfma_f32_32x32x16_bf16 v[2:17], v[2:5], v[62:65], 0
	v_mov_b32_e32 v31, v34
	v_mov_b32_e32 v18, v35
	v_mov_b32_e32 v34, v36
	v_mov_b32_e32 v35, v20
	v_mov_b32_e32 v20, v37
	v_mov_b32_e32 v36, v38
	v_mov_b32_e32 v37, v22
	v_mov_b32_e32 v22, v39
	v_mov_b32_e32 v38, v42
	s_nop 2
	v_mov_b32_e32 v39, v2
	v_pk_fma_f32 v[38:39], v[122:123], 0, v[38:39] op_sel:[1,0,0] op_sel_hi:[1,0,1] neg_hi:[1,0,0]
	v_mov_b32_e32 v2, v43
	v_pk_fma_f32 v[38:39], v[122:123], 0, v[38:39] op_sel_hi:[0,0,1]
	v_pk_fma_f32 v[2:3], v[122:123], v[38:39], v[2:3] op_sel:[1,1,0] op_sel_hi:[1,0,1] neg_hi:[1,0,0]
	v_pk_fma_f32 v[32:33], v[26:27], v[28:29], v[32:33] op_sel:[1,0,0] op_sel_hi:[0,1,1]
	v_pk_fma_f32 v[2:3], v[122:123], v[38:39], v[2:3] op_sel_hi:[0,1,1]
	v_mov_b32_e32 v38, v44
	v_mov_b32_e32 v39, v4
	v_pk_fma_f32 v[38:39], v[122:123], v[2:3], v[38:39] op_sel:[1,1,0] op_sel_hi:[1,0,1] neg_hi:[1,0,0]
	v_mov_b32_e32 v4, v45
	v_pk_fma_f32 v[2:3], v[122:123], v[2:3], v[38:39] op_sel_hi:[0,1,1]
	v_pk_fma_f32 v[4:5], v[122:123], v[2:3], v[4:5] op_sel:[1,1,0] op_sel_hi:[1,0,1] neg_hi:[1,0,0]
	v_pk_fma_f32 v[28:29], v[124:125], v[28:29], v[32:33] op_sel:[0,0,1] op_sel_hi:[0,1,0]
	v_pk_fma_f32 v[2:3], v[122:123], v[2:3], v[4:5] op_sel_hi:[0,1,1]
	v_mov_b32_e32 v4, v46
	v_mov_b32_e32 v5, v6
	v_pk_fma_f32 v[4:5], v[122:123], v[2:3], v[4:5] op_sel:[1,1,0] op_sel_hi:[1,0,1] neg_hi:[1,0,0]
	v_mov_b32_e32 v6, v47
	v_pk_fma_f32 v[2:3], v[122:123], v[2:3], v[4:5] op_sel_hi:[0,1,1]
	v_pk_fma_f32 v[4:5], v[122:123], v[2:3], v[6:7] op_sel:[1,1,0] op_sel_hi:[1,0,1] neg_hi:[1,0,0]
	v_pk_fma_f32 v[30:31], v[124:125], v[28:29], v[30:31] op_sel:[1,0,0] neg_lo:[1,0,0]
	v_pk_fma_f32 v[2:3], v[122:123], v[2:3], v[4:5] op_sel_hi:[0,1,1]
	v_mov_b32_e32 v4, v48
	v_mov_b32_e32 v48, v9
	ds_read_b32 v9, v113 offset:64
	v_mov_b32_e32 v5, v8
	v_pk_fma_f32 v[4:5], v[122:123], v[2:3], v[4:5] op_sel:[1,1,0] op_sel_hi:[1,0,1] neg_hi:[1,0,0]
	v_mov_b32_e32 v134, v10
	v_pk_fma_f32 v[4:5], v[122:123], v[2:3], v[4:5] op_sel_hi:[0,1,1]
	v_xor_b32_e32 v3, 0x80000000, v123
	v_mov_b32_e32 v2, v123
	v_mov_b32_e32 v10, v51
	v_mov_b32_e32 v50, v52
	v_mov_b32_e32 v51, v12
	v_mov_b32_e32 v12, v53
	v_mov_b32_e32 v52, v54
	v_mov_b32_e32 v53, v14
	v_mov_b32_e32 v14, v55
	v_mov_b32_e32 v54, v56
	v_mov_b32_e32 v55, v16
	v_mov_b32_e32 v16, v57
	v_pk_fma_f32 v[56:57], v[2:3], v[4:5], v[48:49] op_sel:[1,0,0] op_sel_hi:[0,1,1]
	v_lshlrev_b32_e32 v2, 16, v106
	v_and_b32_e32 v6, 0xffff0000, v106
	v_lshlrev_b32_e32 v7, 16, v107
	v_and_b32_e32 v8, 0xffff0000, v107
	v_pk_fma_f32 v[28:29], v[124:125], v[28:29], v[30:31] op_sel:[0,0,1] op_sel_hi:[0,1,0]
	v_mov_b32_e32 v106, v27
	v_mov_b32_e32 v107, v125
	s_waitcnt lgkmcnt(0)
	v_mul_f32_e32 v2, v9, v2
	v_mul_f32_e32 v6, v9, v6
	v_pk_fma_f32 v[18:19], v[106:107], v[28:29], v[18:19] op_sel:[1,1,0] op_sel_hi:[0,0,1]
	v_lshlrev_b32_e32 v26, 16, v108
	v_mul_f32_e32 v2, v78, v2
	v_mul_f32_e32 v6, v79, v6
	v_pk_fma_f32 v[18:19], v[124:125], v[28:29], v[18:19] op_sel_hi:[0,1,1]
	v_cvt_pk_bf16_f32 v6, v2, v6
	v_mul_f32_e32 v2, v9, v26
	v_pk_fma_f32 v[26:27], v[106:107], v[18:19], v[34:35] op_sel:[1,1,0] op_sel_hi:[0,0,1]
	v_pk_fma_f32 v[18:19], v[124:125], v[18:19], v[26:27] op_sel_hi:[0,1,1]
	v_pk_fma_f32 v[20:21], v[106:107], v[18:19], v[20:21] op_sel:[1,1,0] op_sel_hi:[0,0,1]
	v_pk_fma_f32 v[18:19], v[124:125], v[18:19], v[20:21] op_sel_hi:[0,1,1]
	v_pk_fma_f32 v[20:21], v[106:107], v[18:19], v[36:37] op_sel:[1,1,0] op_sel_hi:[0,0,1]
	v_mul_f32_e32 v7, v9, v7
	v_mul_f32_e32 v8, v9, v8
	v_pk_fma_f32 v[18:19], v[124:125], v[18:19], v[20:21] op_sel_hi:[0,1,1]
	v_and_b32_e32 v38, 0xffff0000, v108
	v_mul_f32_e32 v7, v80, v7
	v_mul_f32_e32 v8, v81, v8
	v_pk_fma_f32 v[20:21], v[106:107], v[18:19], v[22:23] op_sel:[1,1,0] op_sel_hi:[0,0,1]
	v_mov_b32_e32 v133, v24
	v_cvt_pk_bf16_f32 v7, v7, v8
	v_mul_f32_e32 v8, v9, v38
	v_pk_fma_f32 v[18:19], v[124:125], v[18:19], v[20:21] op_sel_hi:[0,1,1]
	v_lshlrev_b32_e32 v39, 16, v109
	v_mul_f32_e32 v2, v66, v2
	v_mul_f32_e32 v8, v67, v8
	v_pk_fma_f32 v[20:21], v[106:107], v[18:19], v[132:133] op_sel:[1,1,0] op_sel_hi:[0,0,1]
	v_mov_b32_e32 v24, v41
	v_cvt_pk_bf16_f32 v8, v2, v8
	v_mul_f32_e32 v2, v9, v39
	v_mul_f32_e32 v9, v9, v40
	v_pk_fma_f32 v[18:19], v[124:125], v[18:19], v[20:21] op_sel_hi:[0,1,1]
	v_mul_f32_e32 v9, v69, v9
	v_pk_fma_f32 v[20:21], v[106:107], v[18:19], v[24:25] op_sel:[1,1,0] op_sel_hi:[0,0,1]
	v_mul_f32_e32 v2, v68, v2
	v_cvt_pk_bf16_f32 v9, v2, v9
	v_pk_fma_f32 v[108:109], v[124:125], v[18:19], v[20:21] op_sel_hi:[0,1,1]
	v_mfma_f32_32x32x16_bf16 v[34:49], v[6:9], v[74:77], 0
	v_fma_f32 v4, v122, v4, v57
	v_fma_f32 v5, v122, v5, v56
	v_mfma_f32_32x32x16_bf16 v[18:33], v[6:9], v[70:73], 0
	s_nop 8
	v_mov_b32_e32 v132, v34
	s_nop 1
	v_mov_b32_e32 v133, v18
	v_pk_fma_f32 v[132:133], v[106:107], v[108:109], v[132:133] op_sel:[1,1,0] op_sel_hi:[0,0,1]
	v_pk_fma_f32 v[108:109], v[124:125], v[108:109], v[132:133] op_sel_hi:[0,1,1]
	v_mov_b32_e32 v34, v19
	v_pk_fma_f32 v[18:19], v[124:125], v[108:109], v[34:35] op_sel:[1,0,0] neg_lo:[1,0,0]
	v_mov_b32_e32 v34, v20
	v_pk_fma_f32 v[18:19], v[124:125], v[108:109], v[18:19] op_sel:[0,0,1] op_sel_hi:[0,1,0]
	v_mov_b32_e32 v35, v36
	v_pk_fma_f32 v[34:35], v[124:125], v[18:19], v[34:35] op_sel:[1,0,0] neg_lo:[1,0,0]
	v_mov_b32_e32 v20, v37
	v_pk_fma_f32 v[18:19], v[124:125], v[18:19], v[34:35] op_sel:[0,0,1] op_sel_hi:[0,1,0]
	v_pk_fma_f32 v[20:21], v[106:107], v[18:19], v[20:21] op_sel:[1,1,0] op_sel_hi:[0,0,1]
	v_pk_fma_f32 v[18:19], v[124:125], v[18:19], v[20:21] op_sel_hi:[0,1,1]
	v_mov_b32_e32 v20, v38
	v_mov_b32_e32 v21, v22
	v_pk_fma_f32 v[20:21], v[106:107], v[18:19], v[20:21] op_sel:[1,1,0] op_sel_hi:[0,0,1]
	v_pk_fma_f32 v[18:19], v[124:125], v[18:19], v[20:21] op_sel_hi:[0,1,1]
	v_mov_b32_e32 v22, v39
	v_pk_fma_f32 v[20:21], v[106:107], v[18:19], v[22:23] op_sel:[1,1,0] op_sel_hi:[0,0,1]
	v_pk_fma_f32 v[18:19], v[124:125], v[18:19], v[20:21] op_sel_hi:[0,1,1]
	v_mov_b32_e32 v20, v40
	v_mov_b32_e32 v21, v24
	v_pk_fma_f32 v[20:21], v[106:107], v[18:19], v[20:21] op_sel:[1,1,0] op_sel_hi:[0,0,1]
	v_pk_fma_f32 v[18:19], v[124:125], v[18:19], v[20:21] op_sel_hi:[0,1,1]
	v_mov_b32_e32 v24, v41
	v_pk_fma_f32 v[20:21], v[106:107], v[18:19], v[24:25] op_sel:[1,1,0] op_sel_hi:[0,0,1]
	v_pk_fma_f32 v[18:19], v[124:125], v[18:19], v[20:21] op_sel_hi:[0,1,1]
	v_mov_b32_e32 v20, v42
	v_mov_b32_e32 v21, v26
	v_pk_fma_f32 v[20:21], v[106:107], v[18:19], v[20:21] op_sel:[1,1,0] op_sel_hi:[0,0,1]
	v_pk_fma_f32 v[18:19], v[124:125], v[18:19], v[20:21] op_sel_hi:[0,1,1]
	v_mov_b32_e32 v26, v43
	v_pk_fma_f32 v[20:21], v[106:107], v[18:19], v[26:27] op_sel:[1,1,0] op_sel_hi:[0,0,1]
	v_pk_fma_f32 v[26:27], v[122:123], v[4:5], v[134:135] op_sel:[1,0,0] neg_lo:[1,0,0]
	v_mov_b32_e32 v108, v3
	v_pk_fma_f32 v[4:5], v[122:123], v[4:5], v[26:27] op_sel:[0,0,1] op_sel_hi:[0,1,0]
	v_mov_b32_e32 v109, v123
	v_pk_fma_f32 v[2:3], v[108:109], v[4:5], v[10:11] op_sel:[1,1,0] op_sel_hi:[0,0,1]
	v_pk_fma_f32 v[2:3], v[122:123], v[4:5], v[2:3] op_sel_hi:[0,1,1]
	v_pk_fma_f32 v[4:5], v[108:109], v[2:3], v[50:51] op_sel:[1,1,0] op_sel_hi:[0,0,1]
	v_pk_fma_f32 v[2:3], v[122:123], v[2:3], v[4:5] op_sel_hi:[0,1,1]
	v_pk_fma_f32 v[4:5], v[108:109], v[2:3], v[12:13] op_sel:[1,1,0] op_sel_hi:[0,0,1]
	v_pk_fma_f32 v[2:3], v[122:123], v[2:3], v[4:5] op_sel_hi:[0,1,1]
	v_pk_fma_f32 v[4:5], v[108:109], v[2:3], v[52:53] op_sel:[1,1,0] op_sel_hi:[0,0,1]
	v_pk_fma_f32 v[2:3], v[122:123], v[2:3], v[4:5] op_sel_hi:[0,1,1]
	v_pk_fma_f32 v[4:5], v[108:109], v[2:3], v[14:15] op_sel:[1,1,0] op_sel_hi:[0,0,1]
	v_pk_fma_f32 v[2:3], v[122:123], v[2:3], v[4:5] op_sel_hi:[0,1,1]
	v_pk_fma_f32 v[18:19], v[124:125], v[18:19], v[20:21] op_sel_hi:[0,1,1]
	v_mov_b32_e32 v20, v44
	v_mov_b32_e32 v21, v28
	v_pk_fma_f32 v[4:5], v[108:109], v[2:3], v[54:55] op_sel:[1,1,0] op_sel_hi:[0,0,1]
	v_pk_fma_f32 v[20:21], v[106:107], v[18:19], v[20:21] op_sel:[1,1,0] op_sel_hi:[0,0,1]
	v_pk_fma_f32 v[2:3], v[122:123], v[2:3], v[4:5] op_sel_hi:[0,1,1]
	v_pk_fma_f32 v[18:19], v[124:125], v[18:19], v[20:21] op_sel_hi:[0,1,1]
	v_mov_b32_e32 v44, v29
	v_pk_fma_f32 v[4:5], v[108:109], v[2:3], v[16:17] op_sel:[1,1,0] op_sel_hi:[0,0,1]
	v_mov_b32_e32 v20, v30
	v_mov_b32_e32 v21, v46
	v_mov_b32_e32 v30, v47
	v_mov_b32_e32 v22, v48
	v_mov_b32_e32 v23, v32
	v_mov_b32_e32 v32, v49
	v_pk_fma_f32 v[24:25], v[124:125], v[18:19], v[44:45] op_sel:[1,0,0] neg_lo:[1,0,0]
	v_mfma_f32_32x32x16_bf16 v[34:49], v[6:9], v[58:61], 0
	v_fma_f32 v26, v122, v2, v4
	v_fma_f32 v27, v122, v3, v5
	v_fma_f32 v18, v124, v18, v25
	v_fma_f32 v19, v124, v19, v24
	v_fma_f32 v20, -v125, v18, v20
	v_fma_f32 v21, v125, v19, v21
	v_pk_fma_f32 v[18:19], v[124:125], v[18:19], v[20:21] op_sel:[0,0,1] op_sel_hi:[0,1,0]
	v_pk_fma_f32 v[20:21], v[106:107], v[18:19], v[30:31] op_sel:[1,1,0] op_sel_hi:[0,0,1]
	v_pk_fma_f32 v[18:19], v[124:125], v[18:19], v[20:21] op_sel_hi:[0,1,1]
	v_mfma_f32_32x32x16_bf16 v[2:17], v[6:9], v[62:65], 0
	s_nop 1
	v_mov_b32_e32 v28, v34
	v_fma_f32 v20, v107, v19, v22
	v_fma_f32 v21, v106, v18, v23
	v_fma_f32 v18, v124, v18, v20
	v_fma_f32 v19, v124, v19, v21
	v_pk_fma_f32 v[20:21], v[106:107], v[18:19], v[32:33] op_sel:[1,1,0] op_sel_hi:[0,0,1]
	v_pk_fma_f32 v[50:51], v[124:125], v[18:19], v[20:21] op_sel_hi:[0,1,1]
	s_nop 2
	v_mov_b32_e32 v29, v2
	v_pk_fma_f32 v[28:29], v[108:109], v[26:27], v[28:29] op_sel:[1,1,0] op_sel_hi:[0,0,1]
	v_pk_fma_f32 v[26:27], v[122:123], v[26:27], v[28:29] op_sel_hi:[0,1,1]
	v_mov_b32_e32 v34, v3
	v_pk_fma_f32 v[2:3], v[122:123], v[26:27], v[34:35] op_sel:[1,0,0] neg_lo:[1,0,0]
	v_and_b32_e32 v28, 0xffff0000, v104
	v_pk_fma_f32 v[2:3], v[122:123], v[26:27], v[2:3] op_sel:[0,0,1] op_sel_hi:[0,1,0]
	v_mov_b32_e32 v26, v4
	v_mov_b32_e32 v27, v36
	v_pk_fma_f32 v[26:27], v[122:123], v[2:3], v[26:27] op_sel:[1,0,0] neg_lo:[1,0,0]
	v_mov_b32_e32 v4, v37
	v_pk_fma_f32 v[2:3], v[122:123], v[2:3], v[26:27] op_sel:[0,0,1] op_sel_hi:[0,1,0]
	v_pk_fma_f32 v[4:5], v[108:109], v[2:3], v[4:5] op_sel:[1,1,0] op_sel_hi:[0,0,1]
	v_pk_fma_f32 v[2:3], v[122:123], v[2:3], v[4:5] op_sel_hi:[0,1,1]
	v_mov_b32_e32 v4, v38
	v_mov_b32_e32 v5, v6
	v_pk_fma_f32 v[4:5], v[108:109], v[2:3], v[4:5] op_sel:[1,1,0] op_sel_hi:[0,0,1]
	v_pk_fma_f32 v[2:3], v[122:123], v[2:3], v[4:5] op_sel_hi:[0,1,1]
	v_mov_b32_e32 v6, v39
	v_pk_fma_f32 v[4:5], v[108:109], v[2:3], v[6:7] op_sel:[1,1,0] op_sel_hi:[0,0,1]
	v_pk_fma_f32 v[2:3], v[122:123], v[2:3], v[4:5] op_sel_hi:[0,1,1]
	v_mov_b32_e32 v4, v40
	v_mov_b32_e32 v5, v8
	v_pk_fma_f32 v[4:5], v[108:109], v[2:3], v[4:5] op_sel:[1,1,0] op_sel_hi:[0,0,1]
	v_pk_fma_f32 v[2:3], v[122:123], v[2:3], v[4:5] op_sel_hi:[0,1,1]
	v_mov_b32_e32 v8, v41
	v_pk_fma_f32 v[4:5], v[108:109], v[2:3], v[8:9] op_sel:[1,1,0] op_sel_hi:[0,0,1]
	v_pk_fma_f32 v[2:3], v[122:123], v[2:3], v[4:5] op_sel_hi:[0,1,1]
	v_mov_b32_e32 v4, v42
	v_mov_b32_e32 v5, v10
	v_pk_fma_f32 v[4:5], v[108:109], v[2:3], v[4:5] op_sel:[1,1,0] op_sel_hi:[0,0,1]
	v_pk_fma_f32 v[2:3], v[122:123], v[2:3], v[4:5] op_sel_hi:[0,1,1]
	v_mov_b32_e32 v10, v43
	ds_read_b32 v26, v113 offset:128
	v_pk_fma_f32 v[4:5], v[108:109], v[2:3], v[10:11] op_sel:[1,1,0] op_sel_hi:[0,0,1]
	v_pk_fma_f32 v[2:3], v[122:123], v[2:3], v[4:5] op_sel_hi:[0,1,1]
	v_mov_b32_e32 v4, v44
	v_mov_b32_e32 v5, v12
	v_pk_fma_f32 v[4:5], v[108:109], v[2:3], v[4:5] op_sel:[1,1,0] op_sel_hi:[0,0,1]
	v_pk_fma_f32 v[6:7], v[122:123], v[2:3], v[4:5] op_sel_hi:[0,1,1]
	v_lshlrev_b32_e32 v2, 16, v102
	v_and_b32_e32 v3, 0xffff0000, v102
	v_lshlrev_b32_e32 v4, 16, v103
	v_and_b32_e32 v5, 0xffff0000, v103
	s_waitcnt lgkmcnt(0)
	v_mul_f32_e32 v2, v26, v2
	v_mul_f32_e32 v3, v26, v3
	v_mul_f32_e32 v4, v26, v4
	v_mul_f32_e32 v5, v26, v5
	v_lshlrev_b32_e32 v27, 16, v104
	v_mul_f32_e32 v2, v78, v2
	v_mul_f32_e32 v3, v79, v3
	v_mul_f32_e32 v4, v80, v4
	v_mul_f32_e32 v5, v81, v5
	v_cvt_pk_bf16_f32 v2, v2, v3
	v_cvt_pk_bf16_f32 v3, v4, v5
	v_mul_f32_e32 v4, v26, v27
	v_mul_f32_e32 v5, v26, v28
	v_lshlrev_b32_e32 v29, 16, v105
	v_and_b32_e32 v34, 0xffff0000, v105
	v_mul_f32_e32 v4, v66, v4
	v_mul_f32_e32 v5, v67, v5
	v_cvt_pk_bf16_f32 v4, v4, v5
	v_mul_f32_e32 v5, v26, v29
	v_mul_f32_e32 v26, v26, v34
	v_mov_b32_e32 v44, v13
	v_mul_f32_e32 v5, v68, v5
	v_mul_f32_e32 v26, v69, v26
	v_mov_b32_e32 v8, v14
	v_mov_b32_e32 v9, v46
	v_mov_b32_e32 v14, v47
	v_mov_b32_e32 v10, v48
	v_mov_b32_e32 v11, v16
	v_mov_b32_e32 v16, v49
	v_pk_fma_f32 v[12:13], v[122:123], v[6:7], v[44:45] op_sel:[1,0,0] neg_lo:[1,0,0]
	v_cvt_pk_bf16_f32 v5, v5, v26
	s_nop 0
	v_mfma_f32_32x32x16_bf16 v[34:49], v[2:5], v[74:77], 0
	v_fma_f32 v6, v122, v6, v13
	v_fma_f32 v7, v122, v7, v12
	v_fma_f32 v8, -v123, v6, v8
	v_fma_f32 v9, v123, v7, v9
	v_fma_f32 v6, v122, v6, v9
	v_fma_f32 v7, v122, v7, v8
	v_pk_fma_f32 v[8:9], v[108:109], v[6:7], v[14:15] op_sel:[1,1,0] op_sel_hi:[0,0,1]
	v_pk_fma_f32 v[6:7], v[122:123], v[6:7], v[8:9] op_sel_hi:[0,1,1]
	v_pk_fma_f32 v[8:9], v[108:109], v[6:7], v[10:11] op_sel:[1,1,0] op_sel_hi:[0,0,1]
	v_mfma_f32_32x32x16_bf16 v[18:33], v[2:5], v[70:73], 0
	s_nop 1
	v_mov_b32_e32 v52, v34
	v_mov_b32_e32 v34, v36
	v_fma_f32 v6, v122, v6, v8
	v_fma_f32 v7, v122, v7, v9
	v_fma_f32 v8, v109, v7, v16
	v_fma_f32 v9, v108, v6, v17
	v_pk_fma_f32 v[6:7], v[122:123], v[6:7], v[8:9] op_sel_hi:[0,1,1]
	s_nop 2
	v_mov_b32_e32 v53, v18
	v_pk_fma_f32 v[52:53], v[106:107], v[50:51], v[52:53] op_sel:[1,1,0] op_sel_hi:[0,0,1]
	v_pk_fma_f32 v[50:51], v[124:125], v[50:51], v[52:53] op_sel_hi:[0,1,1]
	v_mov_b32_e32 v18, v35
	v_pk_fma_f32 v[18:19], v[106:107], v[50:51], v[18:19] op_sel:[1,1,0] op_sel_hi:[0,0,1]
	v_pk_fma_f32 v[18:19], v[124:125], v[50:51], v[18:19] op_sel_hi:[0,1,1]
	v_mov_b32_e32 v35, v20
	v_pk_fma_f32 v[34:35], v[106:107], v[18:19], v[34:35] op_sel:[1,1,0] op_sel_hi:[0,0,1]
	v_pk_fma_f32 v[18:19], v[124:125], v[18:19], v[34:35] op_sel_hi:[0,1,1]
	v_mov_b32_e32 v20, v37
	v_pk_fma_f32 v[20:21], v[106:107], v[18:19], v[20:21] op_sel:[1,1,0] op_sel_hi:[0,0,1]
	v_pk_fma_f32 v[18:19], v[124:125], v[18:19], v[20:21] op_sel_hi:[0,1,1]
	v_mov_b32_e32 v20, v38
	v_mov_b32_e32 v21, v22
	v_pk_fma_f32 v[20:21], v[106:107], v[18:19], v[20:21] op_sel:[1,1,0] op_sel_hi:[0,0,1]
	v_pk_fma_f32 v[18:19], v[124:125], v[18:19], v[20:21] op_sel_hi:[0,1,1]
	v_mov_b32_e32 v38, v23
	v_pk_fma_f32 v[20:21], v[124:125], v[18:19], v[38:39] op_sel:[1,0,0] neg_lo:[1,0,0]
	v_lshlrev_b32_e32 v50, 16, v100
	v_pk_fma_f32 v[18:19], v[124:125], v[18:19], v[20:21] op_sel:[0,0,1] op_sel_hi:[0,1,0]
	v_mov_b32_e32 v20, v24
	v_mov_b32_e32 v21, v40
	v_pk_fma_f32 v[20:21], v[124:125], v[18:19], v[20:21] op_sel:[1,0,0] neg_lo:[1,0,0]
	v_mov_b32_e32 v24, v41
	v_pk_fma_f32 v[18:19], v[124:125], v[18:19], v[20:21] op_sel:[0,0,1] op_sel_hi:[0,1,0]
	v_pk_fma_f32 v[20:21], v[106:107], v[18:19], v[24:25] op_sel:[1,1,0] op_sel_hi:[0,0,1]
	v_pk_fma_f32 v[18:19], v[124:125], v[18:19], v[20:21] op_sel_hi:[0,1,1]
	v_mov_b32_e32 v20, v42
	v_mov_b32_e32 v21, v26
	v_pk_fma_f32 v[20:21], v[106:107], v[18:19], v[20:21] op_sel:[1,1,0] op_sel_hi:[0,0,1]
	v_pk_fma_f32 v[18:19], v[124:125], v[18:19], v[20:21] op_sel_hi:[0,1,1]
	v_mov_b32_e32 v26, v43
	v_pk_fma_f32 v[20:21], v[106:107], v[18:19], v[26:27] op_sel:[1,1,0] op_sel_hi:[0,0,1]
	v_pk_fma_f32 v[18:19], v[124:125], v[18:19], v[20:21] op_sel_hi:[0,1,1]
	v_mov_b32_e32 v20, v44
	v_mov_b32_e32 v21, v28
	v_pk_fma_f32 v[20:21], v[106:107], v[18:19], v[20:21] op_sel:[1,1,0] op_sel_hi:[0,0,1]
	v_pk_fma_f32 v[18:19], v[124:125], v[18:19], v[20:21] op_sel_hi:[0,1,1]
	v_mov_b32_e32 v28, v45
	v_pk_fma_f32 v[20:21], v[106:107], v[18:19], v[28:29] op_sel:[1,1,0] op_sel_hi:[0,0,1]
	v_pk_fma_f32 v[18:19], v[124:125], v[18:19], v[20:21] op_sel_hi:[0,1,1]
	v_mov_b32_e32 v20, v46
	v_mov_b32_e32 v21, v30
	v_pk_fma_f32 v[20:21], v[106:107], v[18:19], v[20:21] op_sel:[1,1,0] op_sel_hi:[0,0,1]
	v_pk_fma_f32 v[18:19], v[124:125], v[18:19], v[20:21] op_sel_hi:[0,1,1]
	v_mov_b32_e32 v30, v47
	v_pk_fma_f32 v[22:23], v[106:107], v[18:19], v[30:31] op_sel:[1,1,0] op_sel_hi:[0,0,1]
	v_mov_b32_e32 v20, v48
	v_mov_b32_e32 v21, v32
	v_pk_fma_f32 v[18:19], v[124:125], v[18:19], v[22:23] op_sel_hi:[0,1,1]
	v_pk_fma_f32 v[20:21], v[106:107], v[18:19], v[20:21] op_sel:[1,1,0] op_sel_hi:[0,0,1]
	v_mov_b32_e32 v48, v33
	v_pk_fma_f32 v[46:47], v[124:125], v[18:19], v[20:21] op_sel_hi:[0,1,1]
	v_mfma_f32_32x32x16_bf16 v[10:25], v[2:5], v[58:61], 0
	v_lshlrev_b32_e32 v42, 16, v98
	v_and_b32_e32 v43, 0xffff0000, v98
	v_and_b32_e32 v51, 0xffff0000, v100
	v_lshlrev_b32_e32 v44, 16, v99
	v_and_b32_e32 v45, 0xffff0000, v99
	v_lshlrev_b32_e32 v52, 16, v101
	v_and_b32_e32 v53, 0xffff0000, v101
	v_mfma_f32_32x32x16_bf16 v[26:41], v[2:5], v[62:65], 0
	s_nop 3
	v_mov_b32_e32 v8, v10
	v_fma_f32 v48, -v125, v46, v48
	v_fma_f32 v49, v125, v47, v49
	s_nop 4
	v_mov_b32_e32 v9, v26
	v_pk_fma_f32 v[2:3], v[108:109], v[6:7], v[8:9] op_sel:[1,1,0] op_sel_hi:[0,0,1]
	v_pk_fma_f32 v[2:3], v[122:123], v[6:7], v[2:3] op_sel_hi:[0,1,1]
	v_mov_b32_e32 v26, v11
	v_pk_fma_f32 v[4:5], v[108:109], v[2:3], v[26:27] op_sel:[1,1,0] op_sel_hi:[0,0,1]
	v_pk_fma_f32 v[2:3], v[122:123], v[2:3], v[4:5] op_sel_hi:[0,1,1]
	v_mov_b32_e32 v4, v12
	v_mov_b32_e32 v5, v28
	v_pk_fma_f32 v[4:5], v[108:109], v[2:3], v[4:5] op_sel:[1,1,0] op_sel_hi:[0,0,1]
	v_pk_fma_f32 v[2:3], v[122:123], v[2:3], v[4:5] op_sel_hi:[0,1,1]
	v_mov_b32_e32 v28, v13
	v_pk_fma_f32 v[4:5], v[108:109], v[2:3], v[28:29] op_sel:[1,1,0] op_sel_hi:[0,0,1]
	v_pk_fma_f32 v[2:3], v[122:123], v[2:3], v[4:5] op_sel_hi:[0,1,1]
	v_mov_b32_e32 v4, v14
	v_mov_b32_e32 v5, v30
	v_pk_fma_f32 v[4:5], v[108:109], v[2:3], v[4:5] op_sel:[1,1,0] op_sel_hi:[0,0,1]
	v_pk_fma_f32 v[2:3], v[122:123], v[2:3], v[4:5] op_sel_hi:[0,1,1]
	v_mov_b32_e32 v14, v31
	v_pk_fma_f32 v[4:5], v[122:123], v[2:3], v[14:15] op_sel:[1,0,0] neg_lo:[1,0,0]
	ds_read_b32 v6, v113 offset:192
	v_pk_fma_f32 v[2:3], v[122:123], v[2:3], v[4:5] op_sel:[0,0,1] op_sel_hi:[0,1,0]
	v_mov_b32_e32 v4, v32
	v_mov_b32_e32 v5, v16
	v_pk_fma_f32 v[4:5], v[122:123], v[2:3], v[4:5] op_sel:[1,0,0] neg_lo:[1,0,0]
	v_mov_b32_e32 v32, v17
	v_pk_fma_f32 v[2:3], v[122:123], v[2:3], v[4:5] op_sel:[0,0,1] op_sel_hi:[0,1,0]
	v_pk_fma_f32 v[4:5], v[108:109], v[2:3], v[32:33] op_sel:[1,1,0] op_sel_hi:[0,0,1]
	v_pk_fma_f32 v[2:3], v[122:123], v[2:3], v[4:5] op_sel_hi:[0,1,1]
	v_mov_b32_e32 v4, v18
	v_mov_b32_e32 v5, v34
	v_pk_fma_f32 v[4:5], v[108:109], v[2:3], v[4:5] op_sel:[1,1,0] op_sel_hi:[0,0,1]
	v_pk_fma_f32 v[2:3], v[122:123], v[2:3], v[4:5] op_sel_hi:[0,1,1]
	v_mov_b32_e32 v34, v19
	v_pk_fma_f32 v[4:5], v[108:109], v[2:3], v[34:35] op_sel:[1,1,0] op_sel_hi:[0,0,1]
	v_pk_fma_f32 v[2:3], v[122:123], v[2:3], v[4:5] op_sel_hi:[0,1,1]
	v_mov_b32_e32 v4, v20
	v_mov_b32_e32 v5, v36
	v_pk_fma_f32 v[4:5], v[108:109], v[2:3], v[4:5] op_sel:[1,1,0] op_sel_hi:[0,0,1]
	v_pk_fma_f32 v[2:3], v[122:123], v[2:3], v[4:5] op_sel_hi:[0,1,1]
	v_mov_b32_e32 v36, v21
	v_pk_fma_f32 v[4:5], v[108:109], v[2:3], v[36:37] op_sel:[1,1,0] op_sel_hi:[0,0,1]
	v_pk_fma_f32 v[2:3], v[122:123], v[2:3], v[4:5] op_sel_hi:[0,1,1]
	v_mov_b32_e32 v4, v22
	v_mov_b32_e32 v5, v38
	v_pk_fma_f32 v[4:5], v[108:109], v[2:3], v[4:5] op_sel:[1,1,0] op_sel_hi:[0,0,1]
	v_pk_fma_f32 v[2:3], v[122:123], v[2:3], v[4:5] op_sel_hi:[0,1,1]
	s_waitcnt lgkmcnt(0)
	v_mul_f32_e32 v4, v6, v42
	v_mul_f32_e32 v5, v6, v43
	v_mul_f32_e32 v4, v78, v4
	v_mul_f32_e32 v5, v79, v5
	v_cvt_pk_bf16_f32 v42, v4, v5
	v_mul_f32_e32 v4, v6, v50
	v_mul_f32_e32 v5, v6, v51
	v_mul_f32_e32 v7, v6, v44
	v_mul_f32_e32 v8, v6, v45
	v_mul_f32_e32 v4, v66, v4
	v_mul_f32_e32 v5, v67, v5
	v_mul_f32_e32 v7, v80, v7
	v_mul_f32_e32 v8, v81, v8
	v_cvt_pk_bf16_f32 v43, v7, v8
	v_cvt_pk_bf16_f32 v44, v4, v5
	v_mul_f32_e32 v4, v6, v52
	v_mul_f32_e32 v5, v6, v53
	v_mov_b32_e32 v38, v23
	v_mul_f32_e32 v4, v68, v4
	v_mul_f32_e32 v5, v69, v5
	v_pk_fma_f32 v[6:7], v[108:109], v[2:3], v[38:39] op_sel:[1,1,0] op_sel_hi:[0,0,1]
	v_cvt_pk_bf16_f32 v45, v4, v5
	v_mov_b32_e32 v4, v24
	v_mov_b32_e32 v5, v40
	v_pk_fma_f32 v[2:3], v[122:123], v[2:3], v[6:7] op_sel_hi:[0,1,1]
	v_pk_fma_f32 v[4:5], v[108:109], v[2:3], v[4:5] op_sel:[1,1,0] op_sel_hi:[0,0,1]
	v_mov_b32_e32 v24, v41
	v_pk_fma_f32 v[50:51], v[122:123], v[2:3], v[4:5] op_sel_hi:[0,1,1]
	v_mfma_f32_32x32x16_bf16 v[8:23], v[42:45], v[70:73], 0
	v_fma_f32 v52, -v123, v50, v24
	v_fma_f32 v53, v123, v51, v25
	v_fma_f32 v2, v124, v46, v49
	v_fma_f32 v3, v124, v47, v48
	v_fma_f32 v50, v122, v50, v53
	v_fma_f32 v51, v122, v51, v52
	v_mfma_f32_32x32x16_bf16 v[24:39], v[42:45], v[74:77], 0
	s_nop 4
	v_mov_b32_e32 v4, v8
	v_mov_b32_e32 v46, v18
	v_mov_b32_e32 v49, v20
	v_mov_b32_e32 v55, v22
	s_nop 2
	v_mov_b32_e32 v5, v24
	v_pk_fma_f32 v[4:5], v[124:125], v[2:3], v[4:5] op_sel:[1,0,0] neg_lo:[1,0,0]
	v_mov_b32_e32 v8, v25
	v_pk_fma_f32 v[2:3], v[124:125], v[2:3], v[4:5] op_sel:[0,0,1] op_sel_hi:[0,1,0]
	v_pk_fma_f32 v[4:5], v[106:107], v[2:3], v[8:9] op_sel:[1,1,0] op_sel_hi:[0,0,1]
	v_pk_fma_f32 v[2:3], v[124:125], v[2:3], v[4:5] op_sel_hi:[0,1,1]
	v_mov_b32_e32 v4, v26
	v_mov_b32_e32 v5, v10
	v_pk_fma_f32 v[4:5], v[106:107], v[2:3], v[4:5] op_sel:[1,1,0] op_sel_hi:[0,0,1]
	v_pk_fma_f32 v[2:3], v[124:125], v[2:3], v[4:5] op_sel_hi:[0,1,1]
	v_mov_b32_e32 v10, v27
	v_pk_fma_f32 v[4:5], v[106:107], v[2:3], v[10:11] op_sel:[1,1,0] op_sel_hi:[0,0,1]
	v_pk_fma_f32 v[2:3], v[124:125], v[2:3], v[4:5] op_sel_hi:[0,1,1]
	v_mov_b32_e32 v4, v28
	v_mov_b32_e32 v5, v12
	v_pk_fma_f32 v[4:5], v[106:107], v[2:3], v[4:5] op_sel:[1,1,0] op_sel_hi:[0,0,1]
	v_pk_fma_f32 v[2:3], v[124:125], v[2:3], v[4:5] op_sel_hi:[0,1,1]
	v_mov_b32_e32 v12, v29
	v_pk_fma_f32 v[4:5], v[106:107], v[2:3], v[12:13] op_sel:[1,1,0] op_sel_hi:[0,0,1]
	v_pk_fma_f32 v[2:3], v[124:125], v[2:3], v[4:5] op_sel_hi:[0,1,1]
	v_mov_b32_e32 v4, v30
	v_mov_b32_e32 v5, v14
	v_pk_fma_f32 v[4:5], v[106:107], v[2:3], v[4:5] op_sel:[1,1,0] op_sel_hi:[0,0,1]
	v_pk_fma_f32 v[2:3], v[124:125], v[2:3], v[4:5] op_sel_hi:[0,1,1]
	v_mov_b32_e32 v14, v31
	v_pk_fma_f32 v[4:5], v[106:107], v[2:3], v[14:15] op_sel:[1,1,0] op_sel_hi:[0,0,1]
	v_pk_fma_f32 v[2:3], v[124:125], v[2:3], v[4:5] op_sel_hi:[0,1,1]
	v_mov_b32_e32 v4, v32
	v_mov_b32_e32 v5, v16
	v_pk_fma_f32 v[4:5], v[106:107], v[2:3], v[4:5] op_sel:[1,1,0] op_sel_hi:[0,0,1]
	v_pk_fma_f32 v[40:41], v[124:125], v[2:3], v[4:5] op_sel_hi:[0,1,1]
	v_mov_b32_e32 v32, v17
	v_mov_b32_e32 v47, v34
	v_mov_b32_e32 v18, v35
	v_mov_b32_e32 v48, v36
	v_mfma_f32_32x32x16_bf16 v[2:17], v[42:45], v[62:65], 0
	v_mov_b32_e32 v20, v37
	v_mov_b32_e32 v54, v38
	v_mov_b32_e32 v22, v39
	v_fma_f32 v56, -v125, v40, v32
	v_fma_f32 v57, v125, v41, v33
	v_mfma_f32_32x32x16_bf16 v[24:39], v[42:45], v[58:61], 0
	s_nop 5
	v_mov_b32_e32 v52, v2
	s_nop 4
	v_mov_b32_e32 v53, v24
	v_pk_fma_f32 v[42:43], v[122:123], v[50:51], v[52:53] op_sel:[1,0,0] neg_lo:[1,0,0]
	v_mov_b32_e32 v2, v25
	v_pk_fma_f32 v[42:43], v[122:123], v[50:51], v[42:43] op_sel:[0,0,1] op_sel_hi:[0,1,0]
	v_pk_fma_f32 v[2:3], v[108:109], v[42:43], v[2:3] op_sel:[1,1,0] op_sel_hi:[0,0,1]
	v_pk_fma_f32 v[2:3], v[122:123], v[42:43], v[2:3] op_sel_hi:[0,1,1]
	v_mov_b32_e32 v24, v26
	v_mov_b32_e32 v25, v4
	v_pk_fma_f32 v[24:25], v[108:109], v[2:3], v[24:25] op_sel:[1,1,0] op_sel_hi:[0,0,1]
	v_pk_fma_f32 v[2:3], v[122:123], v[2:3], v[24:25] op_sel_hi:[0,1,1]
	v_mov_b32_e32 v4, v27
	v_pk_fma_f32 v[4:5], v[108:109], v[2:3], v[4:5] op_sel:[1,1,0] op_sel_hi:[0,0,1]
	v_pk_fma_f32 v[2:3], v[122:123], v[2:3], v[4:5] op_sel_hi:[0,1,1]
	v_mov_b32_e32 v4, v28
	v_mov_b32_e32 v5, v6
	v_pk_fma_f32 v[4:5], v[108:109], v[2:3], v[4:5] op_sel:[1,1,0] op_sel_hi:[0,0,1]
	v_pk_fma_f32 v[2:3], v[122:123], v[2:3], v[4:5] op_sel_hi:[0,1,1]
	v_mov_b32_e32 v6, v29
	v_pk_fma_f32 v[4:5], v[108:109], v[2:3], v[6:7] op_sel:[1,1,0] op_sel_hi:[0,0,1]
	v_pk_fma_f32 v[2:3], v[122:123], v[2:3], v[4:5] op_sel_hi:[0,1,1]
	v_mov_b32_e32 v4, v30
	v_mov_b32_e32 v5, v8
	v_pk_fma_f32 v[4:5], v[108:109], v[2:3], v[4:5] op_sel:[1,1,0] op_sel_hi:[0,0,1]
	v_pk_fma_f32 v[2:3], v[122:123], v[2:3], v[4:5] op_sel_hi:[0,1,1]
	v_mov_b32_e32 v8, v31
	v_pk_fma_f32 v[4:5], v[108:109], v[2:3], v[8:9] op_sel:[1,1,0] op_sel_hi:[0,0,1]
	ds_read_b32 v9, v113 offset:256
	v_pk_fma_f32 v[2:3], v[122:123], v[2:3], v[4:5] op_sel_hi:[0,1,1]
	v_mov_b32_e32 v4, v32
	v_mov_b32_e32 v5, v10
	v_pk_fma_f32 v[4:5], v[108:109], v[2:3], v[4:5] op_sel:[1,1,0] op_sel_hi:[0,0,1]
	v_pk_fma_f32 v[2:3], v[122:123], v[2:3], v[4:5] op_sel_hi:[0,1,1]
	v_lshlrev_b32_e32 v4, 16, v94
	v_and_b32_e32 v5, 0xffff0000, v94
	v_lshlrev_b32_e32 v6, 16, v95
	v_and_b32_e32 v7, 0xffff0000, v95
	s_waitcnt lgkmcnt(0)
	v_mul_f32_e32 v4, v9, v4
	v_mul_f32_e32 v5, v9, v5
	v_mul_f32_e32 v6, v9, v6
	v_lshlrev_b32_e32 v8, 16, v96
	v_and_b32_e32 v24, 0xffff0000, v96
	v_mul_f32_e32 v4, v78, v4
	v_mul_f32_e32 v5, v79, v5
	v_mul_f32_e32 v27, v80, v6
	v_mul_f32_e32 v6, v9, v7
	v_mul_f32_e32 v7, v81, v6
	v_cvt_pk_bf16_f32 v6, v4, v5
	v_mul_f32_e32 v4, v9, v8
	v_mul_f32_e32 v5, v9, v24
	v_lshlrev_b32_e32 v25, 16, v97
	v_and_b32_e32 v26, 0xffff0000, v97
	v_mul_f32_e32 v4, v66, v4
	v_mul_f32_e32 v5, v67, v5
	v_cvt_pk_bf16_f32 v7, v27, v7
	v_cvt_pk_bf16_f32 v8, v4, v5
	v_mul_f32_e32 v4, v9, v25
	v_mul_f32_e32 v5, v9, v26
	v_mul_f32_e32 v4, v68, v4
	v_mul_f32_e32 v5, v69, v5
	v_cvt_pk_bf16_f32 v9, v4, v5
	v_pk_fma_f32 v[4:5], v[124:125], v[40:41], v[56:57] op_sel:[0,0,1] op_sel_hi:[0,1,0]
	v_pk_fma_f32 v[24:25], v[124:125], v[4:5], v[46:47] op_sel:[1,0,0] neg_lo:[1,0,0]
	v_mov_b32_e32 v32, v11
	v_pk_fma_f32 v[4:5], v[124:125], v[4:5], v[24:25] op_sel:[0,0,1] op_sel_hi:[0,1,0]
	v_pk_fma_f32 v[18:19], v[106:107], v[4:5], v[18:19] op_sel:[1,1,0] op_sel_hi:[0,0,1]
	v_pk_fma_f32 v[4:5], v[124:125], v[4:5], v[18:19] op_sel_hi:[0,1,1]
	v_pk_fma_f32 v[18:19], v[106:107], v[4:5], v[48:49] op_sel:[1,1,0] op_sel_hi:[0,0,1]
	v_pk_fma_f32 v[4:5], v[124:125], v[4:5], v[18:19] op_sel_hi:[0,1,1]
	v_pk_fma_f32 v[18:19], v[106:107], v[4:5], v[20:21] op_sel:[1,1,0] op_sel_hi:[0,0,1]
	v_pk_fma_f32 v[4:5], v[124:125], v[4:5], v[18:19] op_sel_hi:[0,1,1]
	v_pk_fma_f32 v[18:19], v[106:107], v[4:5], v[54:55] op_sel:[1,1,0] op_sel_hi:[0,0,1]
	v_pk_fma_f32 v[4:5], v[124:125], v[4:5], v[18:19] op_sel_hi:[0,1,1]
	v_pk_fma_f32 v[18:19], v[106:107], v[4:5], v[22:23] op_sel:[1,1,0] op_sel_hi:[0,0,1]
	v_mov_b32_e32 v10, v12
	v_mov_b32_e32 v11, v34
	v_mov_b32_e32 v12, v35
	v_mov_b32_e32 v50, v36
	v_mov_b32_e32 v51, v14
	v_mov_b32_e32 v14, v37
	v_mov_b32_e32 v52, v38
	v_mov_b32_e32 v53, v16
	v_mov_b32_e32 v16, v39
	v_pk_fma_f32 v[98:99], v[122:123], v[2:3], v[32:33] op_sel:[1,0,0] neg_lo:[1,0,0]
	v_mfma_f32_32x32x16_bf16 v[34:49], v[6:9], v[74:77], 0
	v_fma_f32 v4, v124, v4, v18
	v_fma_f32 v5, v124, v5, v19
	v_fma_f32 v2, v122, v2, v99
	v_fma_f32 v3, v122, v3, v98
	v_fma_f32 v10, -v123, v2, v10
	v_fma_f32 v11, v123, v3, v11
	v_lshlrev_b32_e32 v56, 16, v93
	v_pk_fma_f32 v[2:3], v[122:123], v[2:3], v[10:11] op_sel:[0,0,1] op_sel_hi:[0,1,0]
	v_pk_fma_f32 v[10:11], v[108:109], v[2:3], v[12:13] op_sel:[1,1,0] op_sel_hi:[0,0,1]
	v_pk_fma_f32 v[2:3], v[122:123], v[2:3], v[10:11] op_sel_hi:[0,1,1]
	v_mfma_f32_32x32x16_bf16 v[18:33], v[6:9], v[70:73], 0
	s_nop 0
	v_mov_b32_e32 v54, v34
	v_fma_f32 v10, v109, v3, v50
	v_fma_f32 v11, v108, v2, v51
	v_fma_f32 v2, v122, v2, v10
	v_fma_f32 v3, v122, v3, v11
	v_pk_fma_f32 v[10:11], v[108:109], v[2:3], v[14:15] op_sel:[1,1,0] op_sel_hi:[0,0,1]
	v_pk_fma_f32 v[2:3], v[122:123], v[2:3], v[10:11] op_sel_hi:[0,1,1]
	v_pk_fma_f32 v[10:11], v[108:109], v[2:3], v[52:53] op_sel:[1,1,0] op_sel_hi:[0,0,1]
	v_pk_fma_f32 v[2:3], v[122:123], v[2:3], v[10:11] op_sel_hi:[0,1,1]
	s_nop 1
	v_mov_b32_e32 v55, v18
	v_pk_fma_f32 v[54:55], v[106:107], v[4:5], v[54:55] op_sel:[1,1,0] op_sel_hi:[0,0,1]
	v_pk_fma_f32 v[4:5], v[124:125], v[4:5], v[54:55] op_sel_hi:[0,1,1]
	v_mov_b32_e32 v18, v35
	v_pk_fma_f32 v[18:19], v[106:107], v[4:5], v[18:19] op_sel:[1,1,0] op_sel_hi:[0,0,1]
	v_pk_fma_f32 v[4:5], v[124:125], v[4:5], v[18:19] op_sel_hi:[0,1,1]
	v_mov_b32_e32 v18, v36
	v_mov_b32_e32 v19, v20
	v_pk_fma_f32 v[18:19], v[106:107], v[4:5], v[18:19] op_sel:[1,1,0] op_sel_hi:[0,0,1]
	v_pk_fma_f32 v[4:5], v[124:125], v[4:5], v[18:19] op_sel_hi:[0,1,1]
	v_mov_b32_e32 v36, v21
	v_pk_fma_f32 v[18:19], v[124:125], v[4:5], v[36:37] op_sel:[1,0,0] neg_lo:[1,0,0]
	v_pk_fma_f32 v[10:11], v[108:109], v[2:3], v[16:17] op_sel:[1,1,0] op_sel_hi:[0,0,1]
	v_pk_fma_f32 v[4:5], v[124:125], v[4:5], v[18:19] op_sel:[0,0,1] op_sel_hi:[0,1,0]
	v_mov_b32_e32 v18, v22
	v_mov_b32_e32 v19, v38
	v_pk_fma_f32 v[18:19], v[124:125], v[4:5], v[18:19] op_sel:[1,0,0] neg_lo:[1,0,0]
	v_mov_b32_e32 v22, v39
	v_pk_fma_f32 v[4:5], v[124:125], v[4:5], v[18:19] op_sel:[0,0,1] op_sel_hi:[0,1,0]
	v_pk_fma_f32 v[18:19], v[106:107], v[4:5], v[22:23] op_sel:[1,1,0] op_sel_hi:[0,0,1]
	v_pk_fma_f32 v[4:5], v[124:125], v[4:5], v[18:19] op_sel_hi:[0,1,1]
	v_mov_b32_e32 v18, v40
	v_mov_b32_e32 v19, v24
	v_pk_fma_f32 v[18:19], v[106:107], v[4:5], v[18:19] op_sel:[1,1,0] op_sel_hi:[0,0,1]
	v_pk_fma_f32 v[4:5], v[124:125], v[4:5], v[18:19] op_sel_hi:[0,1,1]
	v_mov_b32_e32 v24, v41
	v_pk_fma_f32 v[18:19], v[106:107], v[4:5], v[24:25] op_sel:[1,1,0] op_sel_hi:[0,0,1]
	v_pk_fma_f32 v[4:5], v[124:125], v[4:5], v[18:19] op_sel_hi:[0,1,1]
	v_mov_b32_e32 v18, v42
	v_mov_b32_e32 v19, v26
	v_pk_fma_f32 v[18:19], v[106:107], v[4:5], v[18:19] op_sel:[1,1,0] op_sel_hi:[0,0,1]
	v_pk_fma_f32 v[4:5], v[124:125], v[4:5], v[18:19] op_sel_hi:[0,1,1]
	v_mov_b32_e32 v26, v43
	v_pk_fma_f32 v[18:19], v[106:107], v[4:5], v[26:27] op_sel:[1,1,0] op_sel_hi:[0,0,1]
	v_pk_fma_f32 v[4:5], v[124:125], v[4:5], v[18:19] op_sel_hi:[0,1,1]
	v_mov_b32_e32 v18, v44
	v_mov_b32_e32 v19, v28
	v_pk_fma_f32 v[18:19], v[106:107], v[4:5], v[18:19] op_sel:[1,1,0] op_sel_hi:[0,0,1]
	v_pk_fma_f32 v[4:5], v[124:125], v[4:5], v[18:19] op_sel_hi:[0,1,1]
	v_mov_b32_e32 v28, v45
	v_pk_fma_f32 v[18:19], v[106:107], v[4:5], v[28:29] op_sel:[1,1,0] op_sel_hi:[0,0,1]
	v_pk_fma_f32 v[4:5], v[124:125], v[4:5], v[18:19] op_sel_hi:[0,1,1]
	v_mov_b32_e32 v18, v46
	v_mov_b32_e32 v19, v30
	v_pk_fma_f32 v[18:19], v[106:107], v[4:5], v[18:19] op_sel:[1,1,0] op_sel_hi:[0,0,1]
	v_pk_fma_f32 v[4:5], v[124:125], v[4:5], v[18:19] op_sel_hi:[0,1,1]
	v_mov_b32_e32 v46, v31
	v_mov_b32_e32 v28, v32
	v_mov_b32_e32 v29, v48
	v_mov_b32_e32 v32, v49
	v_pk_fma_f32 v[30:31], v[124:125], v[4:5], v[46:47] op_sel:[1,0,0] neg_lo:[1,0,0]
	v_mfma_f32_32x32x16_bf16 v[38:53], v[6:9], v[58:61], 0
	v_fma_f32 v2, v122, v2, v10
	v_fma_f32 v3, v122, v3, v11
	v_lshlrev_b32_e32 v34, 16, v90
	v_and_b32_e32 v35, 0xffff0000, v90
	v_lshlrev_b32_e32 v36, 16, v91
	v_and_b32_e32 v37, 0xffff0000, v91
	v_lshlrev_b32_e32 v54, 16, v92
	v_and_b32_e32 v55, 0xffff0000, v92
	v_mfma_f32_32x32x16_bf16 v[12:27], v[6:9], v[62:65], 0
	s_nop 2
	v_mov_b32_e32 v10, v38
	ds_read_b32 v9, v113 offset:320
	v_and_b32_e32 v57, 0xffff0000, v93
	v_fma_f32 v4, v124, v4, v31
	v_fma_f32 v5, v124, v5, v30
	v_mov_b32_e32 v91, v52
	s_waitcnt lgkmcnt(0)
	v_mul_f32_e32 v8, v9, v36
	s_nop 0
	v_mov_b32_e32 v11, v12
	v_pk_fma_f32 v[6:7], v[108:109], v[2:3], v[10:11] op_sel:[1,1,0] op_sel_hi:[0,0,1]
	v_pk_fma_f32 v[2:3], v[122:123], v[2:3], v[6:7] op_sel_hi:[0,1,1]
	v_mov_b32_e32 v12, v39
	v_pk_fma_f32 v[6:7], v[108:109], v[2:3], v[12:13] op_sel:[1,1,0] op_sel_hi:[0,0,1]
	v_pk_fma_f32 v[2:3], v[122:123], v[2:3], v[6:7] op_sel_hi:[0,1,1]
	v_mov_b32_e32 v6, v40
	v_mov_b32_e32 v7, v14
	v_pk_fma_f32 v[6:7], v[108:109], v[2:3], v[6:7] op_sel:[1,1,0] op_sel_hi:[0,0,1]
	v_pk_fma_f32 v[2:3], v[122:123], v[2:3], v[6:7] op_sel_hi:[0,1,1]
	v_mov_b32_e32 v40, v15
	v_pk_fma_f32 v[6:7], v[122:123], v[2:3], v[40:41] op_sel:[1,0,0] neg_lo:[1,0,0]
	v_mul_f32_e32 v10, v9, v37
	v_pk_fma_f32 v[2:3], v[122:123], v[2:3], v[6:7] op_sel:[0,0,1] op_sel_hi:[0,1,0]
	v_mov_b32_e32 v6, v16
	v_mov_b32_e32 v7, v42
	v_pk_fma_f32 v[6:7], v[122:123], v[2:3], v[6:7] op_sel:[1,0,0] neg_lo:[1,0,0]
	v_mov_b32_e32 v16, v43
	v_pk_fma_f32 v[2:3], v[122:123], v[2:3], v[6:7] op_sel:[0,0,1] op_sel_hi:[0,1,0]
	v_pk_fma_f32 v[6:7], v[108:109], v[2:3], v[16:17] op_sel:[1,1,0] op_sel_hi:[0,0,1]
	v_pk_fma_f32 v[2:3], v[122:123], v[2:3], v[6:7] op_sel_hi:[0,1,1]
	v_mov_b32_e32 v6, v44
	v_mov_b32_e32 v7, v18
	v_pk_fma_f32 v[6:7], v[108:109], v[2:3], v[6:7] op_sel:[1,1,0] op_sel_hi:[0,0,1]
	v_pk_fma_f32 v[2:3], v[122:123], v[2:3], v[6:7] op_sel_hi:[0,1,1]
	v_mov_b32_e32 v18, v45
	v_pk_fma_f32 v[6:7], v[108:109], v[2:3], v[18:19] op_sel:[1,1,0] op_sel_hi:[0,0,1]
	v_pk_fma_f32 v[2:3], v[122:123], v[2:3], v[6:7] op_sel_hi:[0,1,1]
	v_mov_b32_e32 v6, v46
	v_mov_b32_e32 v7, v20
	v_pk_fma_f32 v[6:7], v[108:109], v[2:3], v[6:7] op_sel:[1,1,0] op_sel_hi:[0,0,1]
	v_pk_fma_f32 v[2:3], v[122:123], v[2:3], v[6:7] op_sel_hi:[0,1,1]
	v_mov_b32_e32 v20, v47
	v_pk_fma_f32 v[6:7], v[108:109], v[2:3], v[20:21] op_sel:[1,1,0] op_sel_hi:[0,0,1]
	v_pk_fma_f32 v[2:3], v[122:123], v[2:3], v[6:7] op_sel_hi:[0,1,1]
	v_mov_b32_e32 v6, v48
	v_mov_b32_e32 v7, v22
	v_pk_fma_f32 v[6:7], v[108:109], v[2:3], v[6:7] op_sel:[1,1,0] op_sel_hi:[0,0,1]
	v_pk_fma_f32 v[2:3], v[122:123], v[2:3], v[6:7] op_sel_hi:[0,1,1]
	v_mov_b32_e32 v22, v49
	v_pk_fma_f32 v[6:7], v[108:109], v[2:3], v[22:23] op_sel:[1,1,0] op_sel_hi:[0,0,1]
	v_pk_fma_f32 v[2:3], v[122:123], v[2:3], v[6:7] op_sel_hi:[0,1,1]
	v_mov_b32_e32 v6, v50
	v_mov_b32_e32 v7, v24
	v_pk_fma_f32 v[6:7], v[108:109], v[2:3], v[6:7] op_sel:[1,1,0] op_sel_hi:[0,0,1]
	v_pk_fma_f32 v[2:3], v[122:123], v[2:3], v[6:7] op_sel_hi:[0,1,1]
	v_mul_f32_e32 v6, v9, v34
	v_mul_f32_e32 v7, v9, v35
	v_mul_f32_e32 v6, v78, v6
	v_mul_f32_e32 v7, v79, v7
	v_mul_f32_e32 v8, v80, v8
	v_mul_f32_e32 v10, v81, v10
	v_cvt_pk_bf16_f32 v6, v6, v7
	v_cvt_pk_bf16_f32 v7, v8, v10
	v_mul_f32_e32 v8, v9, v54
	v_mul_f32_e32 v10, v9, v55
	v_mul_f32_e32 v8, v66, v8
	v_mul_f32_e32 v10, v67, v10
	v_cvt_pk_bf16_f32 v8, v8, v10
	v_mul_f32_e32 v10, v9, v56
	v_mul_f32_e32 v9, v9, v57
	v_mul_f32_e32 v10, v68, v10
	v_mul_f32_e32 v9, v69, v9
	v_cvt_pk_bf16_f32 v9, v10, v9
	v_pk_fma_f32 v[10:11], v[124:125], v[4:5], v[28:29] op_sel:[1,0,0] neg_lo:[1,0,0]
	v_mov_b32_e32 v50, v25
	v_pk_fma_f32 v[4:5], v[124:125], v[4:5], v[10:11] op_sel:[0,0,1] op_sel_hi:[0,1,0]
	v_pk_fma_f32 v[10:11], v[106:107], v[4:5], v[32:33] op_sel:[1,1,0] op_sel_hi:[0,0,1]
	v_mfma_f32_32x32x16_bf16 v[34:49], v[6:9], v[74:77], 0
	v_fma_f32 v4, v124, v4, v10
	v_fma_f32 v5, v124, v5, v11
	v_fma_f32 v92, -v123, v2, v50
	v_fma_f32 v93, v123, v3, v51
	v_mov_b32_e32 v90, v26
	v_pk_fma_f32 v[2:3], v[122:123], v[2:3], v[92:93] op_sel:[0,0,1] op_sel_hi:[0,1,0]
	v_mov_b32_e32 v26, v53
	s_nop 4
	v_mov_b32_e32 v28, v34
	v_mfma_f32_32x32x16_bf16 v[10:25], v[6:9], v[70:73], 0
	v_mov_b32_e32 v31, v42
	v_mov_b32_e32 v32, v44
	v_mov_b32_e32 v34, v46
	v_mov_b32_e32 v94, v48
	s_nop 7
	v_mov_b32_e32 v29, v10
	v_pk_fma_f32 v[28:29], v[106:107], v[4:5], v[28:29] op_sel:[1,1,0] op_sel_hi:[0,0,1]
	v_pk_fma_f32 v[4:5], v[124:125], v[4:5], v[28:29] op_sel_hi:[0,1,1]
	v_mov_b32_e32 v10, v35
	v_pk_fma_f32 v[10:11], v[106:107], v[4:5], v[10:11] op_sel:[1,1,0] op_sel_hi:[0,0,1]
	v_pk_fma_f32 v[4:5], v[124:125], v[4:5], v[10:11] op_sel_hi:[0,1,1]
	v_mov_b32_e32 v10, v36
	v_mov_b32_e32 v11, v12
	v_pk_fma_f32 v[10:11], v[106:107], v[4:5], v[10:11] op_sel:[1,1,0] op_sel_hi:[0,0,1]
	v_pk_fma_f32 v[4:5], v[124:125], v[4:5], v[10:11] op_sel_hi:[0,1,1]
	v_mov_b32_e32 v12, v37
	v_pk_fma_f32 v[10:11], v[106:107], v[4:5], v[12:13] op_sel:[1,1,0] op_sel_hi:[0,0,1]
	v_pk_fma_f32 v[4:5], v[124:125], v[4:5], v[10:11] op_sel_hi:[0,1,1]
	v_mov_b32_e32 v10, v38
	v_mov_b32_e32 v11, v14
	v_pk_fma_f32 v[10:11], v[106:107], v[4:5], v[10:11] op_sel:[1,1,0] op_sel_hi:[0,0,1]
	v_pk_fma_f32 v[4:5], v[124:125], v[4:5], v[10:11] op_sel_hi:[0,1,1]
	v_mov_b32_e32 v14, v39
	v_pk_fma_f32 v[10:11], v[106:107], v[4:5], v[14:15] op_sel:[1,1,0] op_sel_hi:[0,0,1]
	v_pk_fma_f32 v[4:5], v[124:125], v[4:5], v[10:11] op_sel_hi:[0,1,1]
	v_mov_b32_e32 v10, v40
	v_mov_b32_e32 v11, v16
	v_pk_fma_f32 v[10:11], v[106:107], v[4:5], v[10:11] op_sel:[1,1,0] op_sel_hi:[0,0,1]
	v_pk_fma_f32 v[28:29], v[124:125], v[4:5], v[10:11] op_sel_hi:[0,1,1]
	v_pk_fma_f32 v[4:5], v[122:123], v[2:3], v[90:91] op_sel:[1,0,0] neg_lo:[1,0,0]
	v_mov_b32_e32 v40, v17
	v_pk_fma_f32 v[2:3], v[122:123], v[2:3], v[4:5] op_sel:[0,0,1] op_sel_hi:[0,1,0]
	v_pk_fma_f32 v[4:5], v[108:109], v[2:3], v[26:27] op_sel:[1,1,0] op_sel_hi:[0,0,1]
	v_mov_b32_e32 v30, v18
	v_mov_b32_e32 v18, v43
	v_mov_b32_e32 v33, v20
	v_mov_b32_e32 v20, v45
	v_mov_b32_e32 v35, v22
	v_mov_b32_e32 v22, v47
	v_mov_b32_e32 v95, v24
	v_mov_b32_e32 v24, v49
	v_mfma_f32_32x32x16_bf16 v[42:57], v[6:9], v[58:61], 0
	v_fma_f32 v26, v122, v2, v4
	v_fma_f32 v27, v122, v3, v5
	v_fma_f32 v36, -v125, v28, v40
	v_fma_f32 v37, v125, v29, v41
	v_and_b32_e32 v40, 0xffff0000, v89
	v_mfma_f32_32x32x16_bf16 v[2:17], v[6:9], v[62:65], 0
	s_nop 5
	v_mov_b32_e32 v38, v42
	s_nop 4
	v_mov_b32_e32 v39, v2
	v_pk_fma_f32 v[38:39], v[108:109], v[26:27], v[38:39] op_sel:[1,1,0] op_sel_hi:[0,0,1]
	v_pk_fma_f32 v[26:27], v[122:123], v[26:27], v[38:39] op_sel_hi:[0,1,1]
	v_mov_b32_e32 v2, v43
	v_pk_fma_f32 v[2:3], v[108:109], v[26:27], v[2:3] op_sel:[1,1,0] op_sel_hi:[0,0,1]
	v_pk_fma_f32 v[2:3], v[122:123], v[26:27], v[2:3] op_sel_hi:[0,1,1]
	v_mov_b32_e32 v26, v44
	v_mov_b32_e32 v27, v4
	v_pk_fma_f32 v[26:27], v[108:109], v[2:3], v[26:27] op_sel:[1,1,0] op_sel_hi:[0,0,1]
	v_pk_fma_f32 v[2:3], v[122:123], v[2:3], v[26:27] op_sel_hi:[0,1,1]
	v_mov_b32_e32 v4, v45
	v_pk_fma_f32 v[4:5], v[108:109], v[2:3], v[4:5] op_sel:[1,1,0] op_sel_hi:[0,0,1]
	v_pk_fma_f32 v[2:3], v[122:123], v[2:3], v[4:5] op_sel_hi:[0,1,1]
	v_mov_b32_e32 v4, v46
	v_mov_b32_e32 v5, v6
	v_pk_fma_f32 v[4:5], v[108:109], v[2:3], v[4:5] op_sel:[1,1,0] op_sel_hi:[0,0,1]
	v_pk_fma_f32 v[2:3], v[122:123], v[2:3], v[4:5] op_sel_hi:[0,1,1]
	v_mov_b32_e32 v6, v47
	ds_read_b32 v26, v113 offset:384
	v_pk_fma_f32 v[4:5], v[108:109], v[2:3], v[6:7] op_sel:[1,1,0] op_sel_hi:[0,0,1]
	v_pk_fma_f32 v[2:3], v[122:123], v[2:3], v[4:5] op_sel_hi:[0,1,1]
	v_mov_b32_e32 v4, v48
	v_mov_b32_e32 v5, v8
	v_pk_fma_f32 v[4:5], v[108:109], v[2:3], v[4:5] op_sel:[1,1,0] op_sel_hi:[0,0,1]
	v_pk_fma_f32 v[2:3], v[122:123], v[2:3], v[4:5] op_sel_hi:[0,1,1]
	v_lshlrev_b32_e32 v4, 16, v86
	v_and_b32_e32 v5, 0xffff0000, v86
	v_lshlrev_b32_e32 v6, 16, v87
	v_and_b32_e32 v7, 0xffff0000, v87
	s_waitcnt lgkmcnt(0)
	v_mul_f32_e32 v4, v26, v4
	v_mul_f32_e32 v5, v26, v5
	v_mul_f32_e32 v6, v26, v6
	v_mul_f32_e32 v7, v26, v7
	v_lshlrev_b32_e32 v27, 16, v88
	v_and_b32_e32 v38, 0xffff0000, v88
	v_mul_f32_e32 v4, v78, v4
	v_mul_f32_e32 v5, v79, v5
	v_mul_f32_e32 v6, v80, v6
	v_mul_f32_e32 v7, v81, v7
	v_cvt_pk_bf16_f32 v4, v4, v5
	v_cvt_pk_bf16_f32 v5, v6, v7
	v_mul_f32_e32 v6, v26, v27
	v_mul_f32_e32 v7, v26, v38
	v_lshlrev_b32_e32 v39, 16, v89
	v_mul_f32_e32 v6, v66, v6
	v_mul_f32_e32 v7, v67, v7
	v_cvt_pk_bf16_f32 v6, v6, v7
	v_mul_f32_e32 v7, v26, v39
	v_mul_f32_e32 v26, v26, v40
	v_mul_f32_e32 v7, v68, v7
	v_mul_f32_e32 v26, v69, v26
	v_cvt_pk_bf16_f32 v7, v7, v26
	v_pk_fma_f32 v[26:27], v[124:125], v[28:29], v[36:37] op_sel:[0,0,1] op_sel_hi:[0,1,0]
	v_pk_fma_f32 v[28:29], v[124:125], v[26:27], v[30:31] op_sel:[1,0,0] neg_lo:[1,0,0]
	v_mov_b32_e32 v48, v9
	v_pk_fma_f32 v[26:27], v[124:125], v[26:27], v[28:29] op_sel:[0,0,1] op_sel_hi:[0,1,0]
	v_pk_fma_f32 v[18:19], v[106:107], v[26:27], v[18:19] op_sel:[1,1,0] op_sel_hi:[0,0,1]
	v_pk_fma_f32 v[18:19], v[124:125], v[26:27], v[18:19] op_sel_hi:[0,1,1]
	v_pk_fma_f32 v[26:27], v[106:107], v[18:19], v[32:33] op_sel:[1,1,0] op_sel_hi:[0,0,1]
	v_pk_fma_f32 v[18:19], v[124:125], v[18:19], v[26:27] op_sel_hi:[0,1,1]
	v_pk_fma_f32 v[20:21], v[106:107], v[18:19], v[20:21] op_sel:[1,1,0] op_sel_hi:[0,0,1]
	v_pk_fma_f32 v[18:19], v[124:125], v[18:19], v[20:21] op_sel_hi:[0,1,1]
	v_pk_fma_f32 v[20:21], v[106:107], v[18:19], v[34:35] op_sel:[1,1,0] op_sel_hi:[0,0,1]
	v_pk_fma_f32 v[18:19], v[124:125], v[18:19], v[20:21] op_sel_hi:[0,1,1]
	v_pk_fma_f32 v[20:21], v[106:107], v[18:19], v[22:23] op_sel:[1,1,0] op_sel_hi:[0,0,1]
	v_pk_fma_f32 v[18:19], v[124:125], v[18:19], v[20:21] op_sel_hi:[0,1,1]
	v_pk_fma_f32 v[20:21], v[106:107], v[18:19], v[94:95] op_sel:[1,1,0] op_sel_hi:[0,0,1]
	v_pk_fma_f32 v[18:19], v[124:125], v[18:19], v[20:21] op_sel_hi:[0,1,1]
	v_pk_fma_f32 v[20:21], v[106:107], v[18:19], v[24:25] op_sel:[1,1,0] op_sel_hi:[0,0,1]
	v_mov_b32_e32 v8, v10
	v_mov_b32_e32 v9, v50
	v_mov_b32_e32 v10, v51
	v_mov_b32_e32 v50, v52
	v_mov_b32_e32 v51, v12
	v_mov_b32_e32 v12, v53
	v_mov_b32_e32 v52, v54
	v_mov_b32_e32 v53, v14
	v_mov_b32_e32 v14, v55
	v_mov_b32_e32 v54, v56
	v_mov_b32_e32 v55, v16
	v_mov_b32_e32 v16, v57
	v_pk_fma_f32 v[56:57], v[122:123], v[2:3], v[48:49] op_sel:[1,0,0] neg_lo:[1,0,0]
	v_mfma_f32_32x32x16_bf16 v[34:49], v[4:7], v[74:77], 0
	v_fma_f32 v86, v124, v18, v20
	v_fma_f32 v87, v124, v19, v21
	v_fma_f32 v2, v122, v2, v57
	v_fma_f32 v3, v122, v3, v56
	v_fma_f32 v8, -v123, v2, v8
	v_fma_f32 v9, v123, v3, v9
	v_pk_fma_f32 v[2:3], v[122:123], v[2:3], v[8:9] op_sel:[0,0,1] op_sel_hi:[0,1,0]
	v_pk_fma_f32 v[8:9], v[108:109], v[2:3], v[10:11] op_sel:[1,1,0] op_sel_hi:[0,0,1]
	v_pk_fma_f32 v[2:3], v[122:123], v[2:3], v[8:9] op_sel_hi:[0,1,1]
	v_mfma_f32_32x32x16_bf16 v[18:33], v[4:7], v[70:73], 0
	s_nop 1
	v_mov_b32_e32 v88, v34
	v_fma_f32 v8, v109, v3, v50
	v_fma_f32 v9, v108, v2, v51
	v_fma_f32 v2, v122, v2, v8
	v_fma_f32 v3, v122, v3, v9
	v_pk_fma_f32 v[8:9], v[108:109], v[2:3], v[12:13] op_sel:[1,1,0] op_sel_hi:[0,0,1]
	v_pk_fma_f32 v[2:3], v[122:123], v[2:3], v[8:9] op_sel_hi:[0,1,1]
	v_pk_fma_f32 v[8:9], v[108:109], v[2:3], v[52:53] op_sel:[1,1,0] op_sel_hi:[0,0,1]
	v_pk_fma_f32 v[2:3], v[122:123], v[2:3], v[8:9] op_sel_hi:[0,1,1]
	s_nop 0
	v_mov_b32_e32 v89, v18
	v_pk_fma_f32 v[88:89], v[106:107], v[86:87], v[88:89] op_sel:[1,1,0] op_sel_hi:[0,0,1]
	v_pk_fma_f32 v[86:87], v[124:125], v[86:87], v[88:89] op_sel_hi:[0,1,1]
	v_mov_b32_e32 v34, v19
	v_pk_fma_f32 v[18:19], v[124:125], v[86:87], v[34:35] op_sel:[1,0,0] neg_lo:[1,0,0]
	v_mov_b32_e32 v34, v20
	v_pk_fma_f32 v[18:19], v[124:125], v[86:87], v[18:19] op_sel:[0,0,1] op_sel_hi:[0,1,0]
	v_mov_b32_e32 v35, v36
	v_pk_fma_f32 v[34:35], v[124:125], v[18:19], v[34:35] op_sel:[1,0,0] neg_lo:[1,0,0]
	v_mov_b32_e32 v20, v37
	v_pk_fma_f32 v[18:19], v[124:125], v[18:19], v[34:35] op_sel:[0,0,1] op_sel_hi:[0,1,0]
	v_pk_fma_f32 v[20:21], v[106:107], v[18:19], v[20:21] op_sel:[1,1,0] op_sel_hi:[0,0,1]
	v_pk_fma_f32 v[18:19], v[124:125], v[18:19], v[20:21] op_sel_hi:[0,1,1]
	v_mov_b32_e32 v20, v38
	v_mov_b32_e32 v21, v22
	v_pk_fma_f32 v[20:21], v[106:107], v[18:19], v[20:21] op_sel:[1,1,0] op_sel_hi:[0,0,1]
	v_pk_fma_f32 v[18:19], v[124:125], v[18:19], v[20:21] op_sel_hi:[0,1,1]
	v_mov_b32_e32 v22, v39
	v_pk_fma_f32 v[20:21], v[106:107], v[18:19], v[22:23] op_sel:[1,1,0] op_sel_hi:[0,0,1]
	v_pk_fma_f32 v[18:19], v[124:125], v[18:19], v[20:21] op_sel_hi:[0,1,1]
	v_mov_b32_e32 v20, v40
	v_mov_b32_e32 v21, v24
	v_pk_fma_f32 v[20:21], v[106:107], v[18:19], v[20:21] op_sel:[1,1,0] op_sel_hi:[0,0,1]
	v_pk_fma_f32 v[18:19], v[124:125], v[18:19], v[20:21] op_sel_hi:[0,1,1]
	v_mov_b32_e32 v24, v41
	v_pk_fma_f32 v[20:21], v[106:107], v[18:19], v[24:25] op_sel:[1,1,0] op_sel_hi:[0,0,1]
	v_pk_fma_f32 v[18:19], v[124:125], v[18:19], v[20:21] op_sel_hi:[0,1,1]
	v_mov_b32_e32 v20, v42
	v_mov_b32_e32 v21, v26
	v_pk_fma_f32 v[20:21], v[106:107], v[18:19], v[20:21] op_sel:[1,1,0] op_sel_hi:[0,0,1]
	v_pk_fma_f32 v[18:19], v[124:125], v[18:19], v[20:21] op_sel_hi:[0,1,1]
	v_mov_b32_e32 v26, v43
	v_pk_fma_f32 v[8:9], v[108:109], v[2:3], v[14:15] op_sel:[1,1,0] op_sel_hi:[0,0,1]
	v_pk_fma_f32 v[20:21], v[106:107], v[18:19], v[26:27] op_sel:[1,1,0] op_sel_hi:[0,0,1]
	v_pk_fma_f32 v[2:3], v[122:123], v[2:3], v[8:9] op_sel_hi:[0,1,1]
	v_pk_fma_f32 v[18:19], v[124:125], v[18:19], v[20:21] op_sel_hi:[0,1,1]
	v_mov_b32_e32 v20, v44
	v_mov_b32_e32 v21, v28
	v_pk_fma_f32 v[8:9], v[108:109], v[2:3], v[54:55] op_sel:[1,1,0] op_sel_hi:[0,0,1]
	v_pk_fma_f32 v[20:21], v[106:107], v[18:19], v[20:21] op_sel:[1,1,0] op_sel_hi:[0,0,1]
	v_pk_fma_f32 v[2:3], v[122:123], v[2:3], v[8:9] op_sel_hi:[0,1,1]
	v_pk_fma_f32 v[18:19], v[124:125], v[18:19], v[20:21] op_sel_hi:[0,1,1]
	v_mov_b32_e32 v44, v29
	v_pk_fma_f32 v[8:9], v[108:109], v[2:3], v[16:17] op_sel:[1,1,0] op_sel_hi:[0,0,1]
	v_mov_b32_e32 v20, v30
	v_mov_b32_e32 v21, v46
	v_mov_b32_e32 v30, v47
	v_mov_b32_e32 v22, v48
	v_mov_b32_e32 v23, v32
	v_mov_b32_e32 v32, v49
	v_pk_fma_f32 v[24:25], v[124:125], v[18:19], v[44:45] op_sel:[1,0,0] neg_lo:[1,0,0]
	v_mfma_f32_32x32x16_bf16 v[34:49], v[4:7], v[58:61], 0
	v_fma_f32 v26, v122, v2, v8
	v_fma_f32 v27, v122, v3, v9
	v_fma_f32 v18, v124, v18, v25
	v_fma_f32 v19, v124, v19, v24
	v_fma_f32 v20, -v125, v18, v20
	v_fma_f32 v21, v125, v19, v21
	v_pk_fma_f32 v[18:19], v[124:125], v[18:19], v[20:21] op_sel:[0,0,1] op_sel_hi:[0,1,0]
	v_pk_fma_f32 v[20:21], v[106:107], v[18:19], v[30:31] op_sel:[1,1,0] op_sel_hi:[0,0,1]
	v_pk_fma_f32 v[18:19], v[124:125], v[18:19], v[20:21] op_sel_hi:[0,1,1]
	v_mfma_f32_32x32x16_bf16 v[2:17], v[4:7], v[62:65], 0
	s_nop 1
	v_mov_b32_e32 v28, v34
	v_fma_f32 v20, v107, v19, v22
	v_fma_f32 v21, v106, v18, v23
	v_fma_f32 v18, v124, v18, v20
	v_fma_f32 v19, v124, v19, v21
	v_pk_fma_f32 v[20:21], v[106:107], v[18:19], v[32:33] op_sel:[1,1,0] op_sel_hi:[0,0,1]
	v_pk_fma_f32 v[50:51], v[124:125], v[18:19], v[20:21] op_sel_hi:[0,1,1]
	s_nop 2
	v_mov_b32_e32 v29, v2
	v_pk_fma_f32 v[28:29], v[108:109], v[26:27], v[28:29] op_sel:[1,1,0] op_sel_hi:[0,0,1]
	v_pk_fma_f32 v[26:27], v[122:123], v[26:27], v[28:29] op_sel_hi:[0,1,1]
	v_mov_b32_e32 v34, v3
	v_pk_fma_f32 v[2:3], v[122:123], v[26:27], v[34:35] op_sel:[1,0,0] neg_lo:[1,0,0]
	v_and_b32_e32 v28, 0xffff0000, v84
	v_pk_fma_f32 v[2:3], v[122:123], v[26:27], v[2:3] op_sel:[0,0,1] op_sel_hi:[0,1,0]
	v_mov_b32_e32 v26, v4
	v_mov_b32_e32 v27, v36
	v_pk_fma_f32 v[26:27], v[122:123], v[2:3], v[26:27] op_sel:[1,0,0] neg_lo:[1,0,0]
	v_mov_b32_e32 v4, v37
	v_pk_fma_f32 v[2:3], v[122:123], v[2:3], v[26:27] op_sel:[0,0,1] op_sel_hi:[0,1,0]
	v_pk_fma_f32 v[4:5], v[108:109], v[2:3], v[4:5] op_sel:[1,1,0] op_sel_hi:[0,0,1]
	v_pk_fma_f32 v[2:3], v[122:123], v[2:3], v[4:5] op_sel_hi:[0,1,1]
	v_mov_b32_e32 v4, v38
	v_mov_b32_e32 v5, v6
	v_pk_fma_f32 v[4:5], v[108:109], v[2:3], v[4:5] op_sel:[1,1,0] op_sel_hi:[0,0,1]
	v_pk_fma_f32 v[2:3], v[122:123], v[2:3], v[4:5] op_sel_hi:[0,1,1]
	v_mov_b32_e32 v6, v39
	v_pk_fma_f32 v[4:5], v[108:109], v[2:3], v[6:7] op_sel:[1,1,0] op_sel_hi:[0,0,1]
	v_pk_fma_f32 v[2:3], v[122:123], v[2:3], v[4:5] op_sel_hi:[0,1,1]
	v_mov_b32_e32 v4, v40
	v_mov_b32_e32 v5, v8
	v_pk_fma_f32 v[4:5], v[108:109], v[2:3], v[4:5] op_sel:[1,1,0] op_sel_hi:[0,0,1]
	v_pk_fma_f32 v[2:3], v[122:123], v[2:3], v[4:5] op_sel_hi:[0,1,1]
	v_mov_b32_e32 v8, v41
	v_pk_fma_f32 v[4:5], v[108:109], v[2:3], v[8:9] op_sel:[1,1,0] op_sel_hi:[0,0,1]
	v_pk_fma_f32 v[2:3], v[122:123], v[2:3], v[4:5] op_sel_hi:[0,1,1]
	v_mov_b32_e32 v4, v42
	v_mov_b32_e32 v5, v10
	v_pk_fma_f32 v[4:5], v[108:109], v[2:3], v[4:5] op_sel:[1,1,0] op_sel_hi:[0,0,1]
	v_pk_fma_f32 v[2:3], v[122:123], v[2:3], v[4:5] op_sel_hi:[0,1,1]
	v_mov_b32_e32 v10, v43
	v_pk_fma_f32 v[4:5], v[108:109], v[2:3], v[10:11] op_sel:[1,1,0] op_sel_hi:[0,0,1]
	v_pk_fma_f32 v[2:3], v[122:123], v[2:3], v[4:5] op_sel_hi:[0,1,1]
	v_mov_b32_e32 v4, v44
	v_mov_b32_e32 v5, v12
	v_pk_fma_f32 v[4:5], v[108:109], v[2:3], v[4:5] op_sel:[1,1,0] op_sel_hi:[0,0,1]
	v_pk_fma_f32 v[6:7], v[122:123], v[2:3], v[4:5] op_sel_hi:[0,1,1]
	ds_read_b32 v2, v113 offset:448
	v_lshlrev_b32_e32 v3, 16, v82
	v_and_b32_e32 v4, 0xffff0000, v82
	v_lshlrev_b32_e32 v5, 16, v83
	v_and_b32_e32 v26, 0xffff0000, v83
	v_lshlrev_b32_e32 v27, 16, v84
	v_lshlrev_b32_e32 v29, 16, v85
	v_and_b32_e32 v34, 0xffff0000, v85
	s_waitcnt lgkmcnt(0)
	v_mul_f32_e32 v3, v2, v3
	v_mul_f32_e32 v4, v2, v4
	v_mul_f32_e32 v5, v2, v5
	v_mul_f32_e32 v26, v2, v26
	v_mul_f32_e32 v27, v2, v27
	v_mul_f32_e32 v28, v2, v28
	v_mul_f32_e32 v29, v2, v29
	v_mul_f32_e32 v2, v2, v34
	v_mov_b32_e32 v44, v13
	v_mul_f32_e32 v3, v78, v3
	v_mul_f32_e32 v4, v79, v4
	v_mul_f32_e32 v5, v80, v5
	v_mul_f32_e32 v26, v81, v26
	v_mul_f32_e32 v27, v66, v27
	v_mul_f32_e32 v28, v67, v28
	v_mul_f32_e32 v29, v68, v29
	v_mul_f32_e32 v34, v69, v2
	v_mov_b32_e32 v8, v14
	v_mov_b32_e32 v9, v46
	v_mov_b32_e32 v14, v47
	v_mov_b32_e32 v10, v48
	v_mov_b32_e32 v11, v16
	v_mov_b32_e32 v16, v49
	v_pk_fma_f32 v[12:13], v[122:123], v[6:7], v[44:45] op_sel:[1,0,0] neg_lo:[1,0,0]
	v_cvt_pk_bf16_f32 v2, v3, v4
	v_cvt_pk_bf16_f32 v3, v5, v26
	v_cvt_pk_bf16_f32 v4, v27, v28
	v_cvt_pk_bf16_f32 v5, v29, v34
	s_nop 0
	v_mfma_f32_32x32x16_bf16 v[34:49], v[2:5], v[74:77], 0
	v_fma_f32 v6, v122, v6, v13
	v_fma_f32 v7, v122, v7, v12
	v_fma_f32 v8, -v123, v6, v8
	v_fma_f32 v9, v123, v7, v9
	v_fma_f32 v6, v122, v6, v9
	v_fma_f32 v7, v122, v7, v8
	v_pk_fma_f32 v[8:9], v[108:109], v[6:7], v[14:15] op_sel:[1,1,0] op_sel_hi:[0,0,1]
	v_pk_fma_f32 v[6:7], v[122:123], v[6:7], v[8:9] op_sel_hi:[0,1,1]
	v_pk_fma_f32 v[8:9], v[108:109], v[6:7], v[10:11] op_sel:[1,1,0] op_sel_hi:[0,0,1]
	v_mfma_f32_32x32x16_bf16 v[18:33], v[2:5], v[70:73], 0
	s_nop 1
	v_mov_b32_e32 v52, v34
	v_mov_b32_e32 v34, v36
	v_mov_b32_e32 v54, v48
	s_nop 6
	v_mov_b32_e32 v53, v18
	v_pk_fma_f32 v[52:53], v[106:107], v[50:51], v[52:53] op_sel:[1,1,0] op_sel_hi:[0,0,1]
	v_pk_fma_f32 v[50:51], v[124:125], v[50:51], v[52:53] op_sel_hi:[0,1,1]
	v_mov_b32_e32 v18, v35
	v_pk_fma_f32 v[18:19], v[106:107], v[50:51], v[18:19] op_sel:[1,1,0] op_sel_hi:[0,0,1]
	v_pk_fma_f32 v[18:19], v[124:125], v[50:51], v[18:19] op_sel_hi:[0,1,1]
	v_mov_b32_e32 v35, v20
	v_pk_fma_f32 v[34:35], v[106:107], v[18:19], v[34:35] op_sel:[1,1,0] op_sel_hi:[0,0,1]
	v_pk_fma_f32 v[18:19], v[124:125], v[18:19], v[34:35] op_sel_hi:[0,1,1]
	v_mov_b32_e32 v20, v37
	v_pk_fma_f32 v[20:21], v[106:107], v[18:19], v[20:21] op_sel:[1,1,0] op_sel_hi:[0,0,1]
	v_pk_fma_f32 v[18:19], v[124:125], v[18:19], v[20:21] op_sel_hi:[0,1,1]
	v_mov_b32_e32 v20, v38
	v_mov_b32_e32 v21, v22
	v_pk_fma_f32 v[20:21], v[106:107], v[18:19], v[20:21] op_sel:[1,1,0] op_sel_hi:[0,0,1]
	v_pk_fma_f32 v[18:19], v[124:125], v[18:19], v[20:21] op_sel_hi:[0,1,1]
	v_mov_b32_e32 v38, v23
	v_mov_b32_e32 v20, v24
	v_mov_b32_e32 v21, v40
	v_mov_b32_e32 v24, v41
	v_mov_b32_e32 v22, v42
	v_mov_b32_e32 v23, v26
	v_mov_b32_e32 v26, v43
	v_mov_b32_e32 v50, v44
	v_mov_b32_e32 v51, v28
	v_mov_b32_e32 v28, v45
	v_mov_b32_e32 v52, v46
	v_mov_b32_e32 v53, v30
	v_mov_b32_e32 v30, v47
	v_mov_b32_e32 v55, v32
	v_mov_b32_e32 v32, v49
	v_pk_fma_f32 v[56:57], v[124:125], v[18:19], v[38:39] op_sel:[1,0,0] neg_lo:[1,0,0]
	v_mfma_f32_32x32x16_bf16 v[34:49], v[2:5], v[62:65], 0
	v_fma_f32 v62, v122, v6, v8
	v_fma_f32 v63, v122, v7, v9
	v_fma_f32 v64, v109, v63, v16
	v_fma_f32 v65, v108, v62, v17
	v_mfma_f32_32x32x16_bf16 v[2:17], v[2:5], v[58:61], 0
	v_fma_f32 v58, v122, v62, v64
	v_fma_f32 v59, v122, v63, v65
	s_nop 4
	v_mov_b32_e32 v61, v34
	s_nop 3
	v_mov_b32_e32 v60, v2
	v_pk_fma_f32 v[60:61], v[108:109], v[58:59], v[60:61] op_sel:[1,1,0] op_sel_hi:[0,0,1]
	v_pk_fma_f32 v[58:59], v[122:123], v[58:59], v[60:61] op_sel_hi:[0,1,1]
	v_mov_b32_e32 v34, v3
	v_pk_fma_f32 v[2:3], v[108:109], v[58:59], v[34:35] op_sel:[1,1,0] op_sel_hi:[0,0,1]
	v_pk_fma_f32 v[2:3], v[122:123], v[58:59], v[2:3] op_sel_hi:[0,1,1]
	v_mov_b32_e32 v34, v4
	v_mov_b32_e32 v35, v36
	v_pk_fma_f32 v[34:35], v[108:109], v[2:3], v[34:35] op_sel:[1,1,0] op_sel_hi:[0,0,1]
	v_pk_fma_f32 v[2:3], v[122:123], v[2:3], v[34:35] op_sel_hi:[0,1,1]
	v_mov_b32_e32 v36, v5
	v_pk_fma_f32 v[4:5], v[108:109], v[2:3], v[36:37] op_sel:[1,1,0] op_sel_hi:[0,0,1]
	v_pk_fma_f32 v[2:3], v[122:123], v[2:3], v[4:5] op_sel_hi:[0,1,1]
	v_mov_b32_e32 v4, v6
	v_mov_b32_e32 v5, v38
	v_pk_fma_f32 v[4:5], v[108:109], v[2:3], v[4:5] op_sel:[1,1,0] op_sel_hi:[0,0,1]
	v_pk_fma_f32 v[2:3], v[122:123], v[2:3], v[4:5] op_sel_hi:[0,1,1]
	v_mov_b32_e32 v6, v39
	v_pk_fma_f32 v[4:5], v[122:123], v[2:3], v[6:7] op_sel:[1,0,0] neg_lo:[1,0,0]
	v_pk_fma_f32 v[6:7], v[124:125], v[18:19], v[56:57] op_sel:[0,0,1] op_sel_hi:[0,1,0]
	v_pk_fma_f32 v[2:3], v[122:123], v[2:3], v[4:5] op_sel:[0,0,1] op_sel_hi:[0,1,0]
	v_mov_b32_e32 v4, v40
	v_mov_b32_e32 v5, v8
	v_pk_fma_f32 v[20:21], v[124:125], v[6:7], v[20:21] op_sel:[1,0,0] neg_lo:[1,0,0]
	v_pk_fma_f32 v[4:5], v[122:123], v[2:3], v[4:5] op_sel:[1,0,0] neg_lo:[1,0,0]
	v_pk_fma_f32 v[6:7], v[124:125], v[6:7], v[20:21] op_sel:[0,0,1] op_sel_hi:[0,1,0]
	v_pk_fma_f32 v[2:3], v[122:123], v[2:3], v[4:5] op_sel:[0,0,1] op_sel_hi:[0,1,0]
	v_mov_b32_e32 v40, v9
	v_pk_fma_f32 v[20:21], v[106:107], v[6:7], v[24:25] op_sel:[1,1,0] op_sel_hi:[0,0,1]
	v_pk_fma_f32 v[4:5], v[108:109], v[2:3], v[40:41] op_sel:[1,1,0] op_sel_hi:[0,0,1]
	v_pk_fma_f32 v[6:7], v[124:125], v[6:7], v[20:21] op_sel_hi:[0,1,1]
	v_pk_fma_f32 v[2:3], v[122:123], v[2:3], v[4:5] op_sel_hi:[0,1,1]
	v_mov_b32_e32 v4, v10
	v_mov_b32_e32 v5, v42
	v_pk_fma_f32 v[20:21], v[106:107], v[6:7], v[22:23] op_sel:[1,1,0] op_sel_hi:[0,0,1]
	v_pk_fma_f32 v[4:5], v[108:109], v[2:3], v[4:5] op_sel:[1,1,0] op_sel_hi:[0,0,1]
	v_pk_fma_f32 v[6:7], v[124:125], v[6:7], v[20:21] op_sel_hi:[0,1,1]
	v_pk_fma_f32 v[2:3], v[122:123], v[2:3], v[4:5] op_sel_hi:[0,1,1]
	v_mov_b32_e32 v42, v11
	v_pk_fma_f32 v[20:21], v[106:107], v[6:7], v[26:27] op_sel:[1,1,0] op_sel_hi:[0,0,1]
	v_pk_fma_f32 v[4:5], v[108:109], v[2:3], v[42:43] op_sel:[1,1,0] op_sel_hi:[0,0,1]
	v_pk_fma_f32 v[6:7], v[124:125], v[6:7], v[20:21] op_sel_hi:[0,1,1]
	v_pk_fma_f32 v[2:3], v[122:123], v[2:3], v[4:5] op_sel_hi:[0,1,1]
	v_mov_b32_e32 v4, v12
	v_mov_b32_e32 v5, v44
	v_pk_fma_f32 v[20:21], v[106:107], v[6:7], v[50:51] op_sel:[1,1,0] op_sel_hi:[0,0,1]
	v_pk_fma_f32 v[4:5], v[108:109], v[2:3], v[4:5] op_sel:[1,1,0] op_sel_hi:[0,0,1]
	v_pk_fma_f32 v[6:7], v[124:125], v[6:7], v[20:21] op_sel_hi:[0,1,1]
	v_pk_fma_f32 v[2:3], v[122:123], v[2:3], v[4:5] op_sel_hi:[0,1,1]
	v_mov_b32_e32 v44, v13
	v_pk_fma_f32 v[20:21], v[106:107], v[6:7], v[28:29] op_sel:[1,1,0] op_sel_hi:[0,0,1]
	v_pk_fma_f32 v[4:5], v[108:109], v[2:3], v[44:45] op_sel:[1,1,0] op_sel_hi:[0,0,1]
	v_pk_fma_f32 v[6:7], v[124:125], v[6:7], v[20:21] op_sel_hi:[0,1,1]
	v_pk_fma_f32 v[2:3], v[122:123], v[2:3], v[4:5] op_sel_hi:[0,1,1]
	v_mov_b32_e32 v4, v14
	v_mov_b32_e32 v5, v46
	v_pk_fma_f32 v[20:21], v[106:107], v[6:7], v[52:53] op_sel:[1,1,0] op_sel_hi:[0,0,1]
	v_pk_fma_f32 v[4:5], v[108:109], v[2:3], v[4:5] op_sel:[1,1,0] op_sel_hi:[0,0,1]
	v_pk_fma_f32 v[6:7], v[124:125], v[6:7], v[20:21] op_sel_hi:[0,1,1]
	v_pk_fma_f32 v[2:3], v[122:123], v[2:3], v[4:5] op_sel_hi:[0,1,1]
	v_mov_b32_e32 v46, v15
	v_pk_fma_f32 v[20:21], v[106:107], v[6:7], v[30:31] op_sel:[1,1,0] op_sel_hi:[0,0,1]
	v_pk_fma_f32 v[4:5], v[108:109], v[2:3], v[46:47] op_sel:[1,1,0] op_sel_hi:[0,0,1]
	v_lshl_or_b32 v18, s10, 5, v112
	v_pk_fma_f32 v[6:7], v[124:125], v[6:7], v[20:21] op_sel_hi:[0,1,1]
	v_pk_fma_f32 v[2:3], v[122:123], v[2:3], v[4:5] op_sel_hi:[0,1,1]
	v_mov_b32_e32 v4, v16
	v_mov_b32_e32 v5, v48
	v_or_b32_e32 v18, s18, v18
	v_pk_fma_f32 v[20:21], v[106:107], v[6:7], v[54:55] op_sel:[1,1,0] op_sel_hi:[0,0,1]
	v_pk_fma_f32 v[4:5], v[108:109], v[2:3], v[4:5] op_sel:[1,1,0] op_sel_hi:[0,0,1]
	v_lshl_add_u32 v18, v18, 6, s0
	v_pk_fma_f32 v[6:7], v[124:125], v[6:7], v[20:21] op_sel_hi:[0,1,1]
	v_pk_fma_f32 v[2:3], v[122:123], v[2:3], v[4:5] op_sel_hi:[0,1,1]
	v_mov_b32_e32 v48, v17
	v_ashrrev_i32_e32 v19, 31, v18
	v_pk_fma_f32 v[20:21], v[106:107], v[6:7], v[32:33] op_sel:[1,1,0] op_sel_hi:[0,0,1]
	v_pk_fma_f32 v[4:5], v[108:109], v[2:3], v[48:49] op_sel:[1,1,0] op_sel_hi:[0,0,1]
	v_lshlrev_b64 v[18:19], 9, v[18:19]
	v_pk_fma_f32 v[6:7], v[124:125], v[6:7], v[20:21] op_sel_hi:[0,1,1]
	v_pk_fma_f32 v[2:3], v[122:123], v[2:3], v[4:5] op_sel_hi:[0,1,1]
	v_lshl_add_u64 v[18:19], v[120:121], 0, v[18:19]
	v_pk_mov_b32 v[6:7], v[6:7], v[6:7] op_sel:[1,0]
	v_pk_mov_b32 v[2:3], v[2:3], v[2:3] op_sel:[1,0]
	global_store_dwordx2 v[18:19], v[6:7], off
	global_store_dwordx2 v[18:19], v[2:3], off offset:256
	s_cbranch_scc0 .LBB0_175
.LBB0_173:
	s_bfe_u32 s18, s14, 0x40003
	s_ashr_i32 s10, s14, 7
	s_barrier
	s_branch .LBB0_172
